# indexer key conversion for tile blocks 0-6 rewritten compactly (3 integer ops per key, causal select only on the diagonal tile), bit-identical keys
# speedup vs baseline: 1.0044x; 1.0015x over previous
; #define MFMA32(a, b, c) __builtin_amdgcn_mfma_f32_32x32x16_bf16((a), (b), (c), 0, 0, 0)
; DI void a1_task(unsigned char* shm, const bf16_t* prm, const bf16_t* prt, unsigned* mask, int b, int qt, const int tid) {
;     ...
;             for (int hh = 0; hh < 8; ++hh) {
;                 bf16x8 qa[4];
; #pragma unroll
;                 for (int ks = 0; ks < 4; ++ks) qa[ks] = *(const bf16x8*)(qb0 + hh * 128 + 32 * ks);
;                 const float wv = wqs[hh * 32 + r];
;                 asm volatile("s_waitcnt lgkmcnt(0)" ::: "memory");
;                 f32x16 acc;
; #pragma unroll
;                 for (int i = 0; i < 16; ++i) acc[i] = 0.f;
; #pragma unroll
;                 for (int ks = 0; ks < 4; ++ks) acc = MFMA32(kf[ks], qa[ks], acc);
; #pragma unroll
;                 for (int i = 0; i < 16; ++i) idx[i] = fmaf(wv, fmaxf(acc[i], 0.f), idx[i]);
;             }
; #pragma unroll
;             for (int i = 0; i < 16; ++i) {
;                 const int s = s0 + 16 * (i >> 3) + 8 * h + (i & 7);
;                 const unsigned u = __float_as_uint(idx[i] + 0.0f);
;                 const unsigned k = (u & 0x80000000u) ? ~u : (u | 0x80000000u);
;                 key[jt][i] = (s <= t0 + r) ? k : 0u;
;             }
.LBB0_389:
	v_add_u32_e32 v79, s1, v118
	ds_read_b128 v[2:5], v79
	ds_read_b128 v[66:69], v79 offset:32
	ds_read_b128 v[70:73], v79 offset:64
	ds_read_b128 v[74:77], v79 offset:96
	v_add_u32_e32 v80, s1, v135
	s_waitcnt lgkmcnt(3)
	v_mfma_f32_32x32x16_bf16 v[2:17], v[50:53], v[2:5], 0
	ds_read_b32 v78, v80
	s_waitcnt lgkmcnt(0)
	s_addk_i32 s1, 0x100
	s_cmpk_eq_i32 s1, 0x400
	s_waitcnt lgkmcnt(3)
	v_mfma_f32_32x32x16_bf16 v[2:17], v[54:57], v[66:69], v[2:17]
	s_waitcnt lgkmcnt(2)
	v_mfma_f32_32x32x16_bf16 v[2:17], v[58:61], v[70:73], v[2:17]
	s_waitcnt lgkmcnt(1)
	v_mfma_f32_32x32x16_bf16 v[2:17], v[62:65], v[74:77], v[2:17]
	s_nop 11
	v_max_f32_e32 v2, 0, v2
	v_max_f32_e32 v3, 0, v3
	s_waitcnt lgkmcnt(0)
	v_pk_fma_f32 v[48:49], v[78:79], v[2:3], v[48:49] op_sel_hi:[0,1,1]
	v_max_f32_e32 v2, 0, v4
	v_max_f32_e32 v3, 0, v5
	v_pk_fma_f32 v[46:47], v[78:79], v[2:3], v[46:47] op_sel_hi:[0,1,1]
	v_max_f32_e32 v2, 0, v6
	v_max_f32_e32 v3, 0, v7
	v_pk_fma_f32 v[44:45], v[78:79], v[2:3], v[44:45] op_sel_hi:[0,1,1]
	v_max_f32_e32 v2, 0, v8
	v_max_f32_e32 v3, 0, v9
	v_pk_fma_f32 v[42:43], v[78:79], v[2:3], v[42:43] op_sel_hi:[0,1,1]
	v_max_f32_e32 v2, 0, v10
	v_max_f32_e32 v3, 0, v11
	v_pk_fma_f32 v[40:41], v[78:79], v[2:3], v[40:41] op_sel_hi:[0,1,1]
	v_max_f32_e32 v2, 0, v12
	v_max_f32_e32 v3, 0, v13
	v_pk_fma_f32 v[38:39], v[78:79], v[2:3], v[38:39] op_sel_hi:[0,1,1]
	v_max_f32_e32 v2, 0, v14
	v_max_f32_e32 v3, 0, v15
	v_pk_fma_f32 v[36:37], v[78:79], v[2:3], v[36:37] op_sel_hi:[0,1,1]
	v_max_f32_e32 v2, 0, v16
	v_max_f32_e32 v3, 0, v17
	v_pk_fma_f32 v[34:35], v[78:79], v[2:3], v[34:35] op_sel_hi:[0,1,1]
	ds_read_b128 v[2:5], v79 offset:128
	ds_read_b128 v[66:69], v79 offset:160
	ds_read_b128 v[70:73], v79 offset:192
	ds_read_b128 v[74:77], v79 offset:224
	ds_read_b32 v78, v80 offset:128
	s_waitcnt lgkmcnt(4)
	v_mfma_f32_32x32x16_bf16 v[2:17], v[50:53], v[2:5], 0
	s_waitcnt lgkmcnt(0)
	s_waitcnt lgkmcnt(3)
	v_mfma_f32_32x32x16_bf16 v[2:17], v[54:57], v[66:69], v[2:17]
	s_waitcnt lgkmcnt(2)
	v_mfma_f32_32x32x16_bf16 v[2:17], v[58:61], v[70:73], v[2:17]
	s_waitcnt lgkmcnt(1)
	v_mfma_f32_32x32x16_bf16 v[2:17], v[62:65], v[74:77], v[2:17]
	s_nop 11
	v_max_f32_e32 v2, 0, v2
	v_max_f32_e32 v3, 0, v3
	s_waitcnt lgkmcnt(0)
	v_pk_fma_f32 v[48:49], v[78:79], v[2:3], v[48:49] op_sel_hi:[0,1,1]
	v_max_f32_e32 v2, 0, v4
	v_max_f32_e32 v3, 0, v5
	v_pk_fma_f32 v[46:47], v[78:79], v[2:3], v[46:47] op_sel_hi:[0,1,1]
	v_max_f32_e32 v2, 0, v6
	v_max_f32_e32 v3, 0, v7
	v_pk_fma_f32 v[44:45], v[78:79], v[2:3], v[44:45] op_sel_hi:[0,1,1]
	v_max_f32_e32 v2, 0, v8
	v_max_f32_e32 v3, 0, v9
	v_pk_fma_f32 v[42:43], v[78:79], v[2:3], v[42:43] op_sel_hi:[0,1,1]
	v_max_f32_e32 v2, 0, v10
	v_max_f32_e32 v3, 0, v11
	v_pk_fma_f32 v[40:41], v[78:79], v[2:3], v[40:41] op_sel_hi:[0,1,1]
	v_max_f32_e32 v2, 0, v12
	v_max_f32_e32 v3, 0, v13
	v_pk_fma_f32 v[38:39], v[78:79], v[2:3], v[38:39] op_sel_hi:[0,1,1]
	v_max_f32_e32 v2, 0, v14
	v_max_f32_e32 v3, 0, v15
	v_pk_fma_f32 v[36:37], v[78:79], v[2:3], v[36:37] op_sel_hi:[0,1,1]
	v_max_f32_e32 v2, 0, v16
	v_max_f32_e32 v3, 0, v17
	v_pk_fma_f32 v[34:35], v[78:79], v[2:3], v[34:35] op_sel_hi:[0,1,1]
	s_cbranch_scc0 .LBB0_389
	v_or_b32_e32 v8, s0, v98
	s_lshr_b32 s98, s0, 5
	s_cmp_lt_u32 s98, s2
	s_cbranch_scc1 .Lkc_full_389
	v_pk_add_f32 v[2:3], v[48:49], 0 op_sel_hi:[1,0]
	v_ashrrev_i32_e32 v4, 31, v2
	v_ashrrev_i32_e32 v5, 31, v3
	v_or_b32_e32 v4, 0x80000000, v4
	v_or_b32_e32 v5, 0x80000000, v5
	v_xor_b32_e32 v2, v2, v4
	v_xor_b32_e32 v3, v3, v5
	v_mov_b32_e32 v6, v8
	v_cmp_le_i32_e64 s[98:99], v6, v0
	v_or_b32_e32 v7, 1, v8
	s_nop 0
	v_cndmask_b32_e64 v142, 0, v2, s[98:99]
	v_cmp_le_i32_e64 s[98:99], v7, v0
	s_nop 1
	v_cndmask_b32_e64 v141, 0, v3, s[98:99]
	v_pk_add_f32 v[2:3], v[46:47], 0 op_sel_hi:[1,0]
	v_ashrrev_i32_e32 v4, 31, v2
	v_ashrrev_i32_e32 v5, 31, v3
	v_or_b32_e32 v4, 0x80000000, v4
	v_or_b32_e32 v5, 0x80000000, v5
	v_xor_b32_e32 v2, v2, v4
	v_xor_b32_e32 v3, v3, v5
	v_or_b32_e32 v6, 2, v8
	v_cmp_le_i32_e64 s[98:99], v6, v0
	v_or_b32_e32 v7, 3, v8
	s_nop 0
	v_cndmask_b32_e64 v144, 0, v2, s[98:99]
	v_cmp_le_i32_e64 s[98:99], v7, v0
	s_nop 1
	v_cndmask_b32_e64 v143, 0, v3, s[98:99]
	v_pk_add_f32 v[2:3], v[44:45], 0 op_sel_hi:[1,0]
	v_ashrrev_i32_e32 v4, 31, v2
	v_ashrrev_i32_e32 v5, 31, v3
	v_or_b32_e32 v4, 0x80000000, v4
	v_or_b32_e32 v5, 0x80000000, v5
	v_xor_b32_e32 v2, v2, v4
	v_xor_b32_e32 v3, v3, v5
	v_or_b32_e32 v6, 4, v8
	v_cmp_le_i32_e64 s[98:99], v6, v0
	v_or_b32_e32 v7, 5, v8
	s_nop 0
	v_cndmask_b32_e64 v146, 0, v2, s[98:99]
	v_cmp_le_i32_e64 s[98:99], v7, v0
	s_nop 1
	v_cndmask_b32_e64 v145, 0, v3, s[98:99]
	v_pk_add_f32 v[2:3], v[42:43], 0 op_sel_hi:[1,0]
	v_ashrrev_i32_e32 v4, 31, v2
	v_ashrrev_i32_e32 v5, 31, v3
	v_or_b32_e32 v4, 0x80000000, v4
	v_or_b32_e32 v5, 0x80000000, v5
	v_xor_b32_e32 v2, v2, v4
	v_xor_b32_e32 v3, v3, v5
	v_or_b32_e32 v6, 6, v8
	v_cmp_le_i32_e64 s[98:99], v6, v0
	v_or_b32_e32 v7, 7, v8
	s_nop 0
	v_cndmask_b32_e64 v149, 0, v2, s[98:99]
	v_cmp_le_i32_e64 s[98:99], v7, v0
	s_nop 1
	v_cndmask_b32_e64 v147, 0, v3, s[98:99]
	v_pk_add_f32 v[2:3], v[40:41], 0 op_sel_hi:[1,0]
	v_ashrrev_i32_e32 v4, 31, v2
	v_ashrrev_i32_e32 v5, 31, v3
	v_or_b32_e32 v4, 0x80000000, v4
	v_or_b32_e32 v5, 0x80000000, v5
	v_xor_b32_e32 v2, v2, v4
	v_xor_b32_e32 v3, v3, v5
	v_or_b32_e32 v6, 16, v8
	v_cmp_le_i32_e64 s[98:99], v6, v0
	v_or_b32_e32 v7, 17, v8
	s_nop 0
	v_cndmask_b32_e64 v151, 0, v2, s[98:99]
	v_cmp_le_i32_e64 s[98:99], v7, v0
	s_nop 1
	v_cndmask_b32_e64 v150, 0, v3, s[98:99]
	v_pk_add_f32 v[2:3], v[38:39], 0 op_sel_hi:[1,0]
	v_ashrrev_i32_e32 v4, 31, v2
	v_ashrrev_i32_e32 v5, 31, v3
	v_or_b32_e32 v4, 0x80000000, v4
	v_or_b32_e32 v5, 0x80000000, v5
	v_xor_b32_e32 v2, v2, v4
	v_xor_b32_e32 v3, v3, v5
	v_or_b32_e32 v6, 18, v8
	v_cmp_le_i32_e64 s[98:99], v6, v0
	v_or_b32_e32 v7, 19, v8
	s_nop 0
	v_cndmask_b32_e64 v153, 0, v2, s[98:99]
	v_cmp_le_i32_e64 s[98:99], v7, v0
	s_nop 1
	v_cndmask_b32_e64 v152, 0, v3, s[98:99]
	v_pk_add_f32 v[2:3], v[36:37], 0 op_sel_hi:[1,0]
	v_ashrrev_i32_e32 v4, 31, v2
	v_ashrrev_i32_e32 v5, 31, v3
	v_or_b32_e32 v4, 0x80000000, v4
	v_or_b32_e32 v5, 0x80000000, v5
	v_xor_b32_e32 v2, v2, v4
	v_xor_b32_e32 v3, v3, v5
	v_or_b32_e32 v6, 20, v8
	v_cmp_le_i32_e64 s[98:99], v6, v0
	v_or_b32_e32 v7, 21, v8
	s_nop 0
	v_cndmask_b32_e64 v155, 0, v2, s[98:99]
	v_cmp_le_i32_e64 s[98:99], v7, v0
	s_nop 1
	v_cndmask_b32_e64 v154, 0, v3, s[98:99]
	v_pk_add_f32 v[2:3], v[34:35], 0 op_sel_hi:[1,0]
	v_ashrrev_i32_e32 v4, 31, v2
	v_ashrrev_i32_e32 v5, 31, v3
	v_or_b32_e32 v4, 0x80000000, v4
	v_or_b32_e32 v5, 0x80000000, v5
	v_xor_b32_e32 v2, v2, v4
	v_xor_b32_e32 v3, v3, v5
	v_or_b32_e32 v6, 22, v8
	v_cmp_le_i32_e64 s[98:99], v6, v0
	v_or_b32_e32 v7, 23, v8
	s_nop 0
	v_cndmask_b32_e64 v157, 0, v2, s[98:99]
	v_cmp_le_i32_e64 s[98:99], v7, v0
	s_nop 1
	v_cndmask_b32_e64 v156, 0, v3, s[98:99]
	s_branch .Lkc_done_389
; DI void a1_task(unsigned char* shm, const bf16_t* prm, const bf16_t* prt, unsigned* mask, int b, int qt, const int tid) {
;     ...
;             for (int i = 0; i < 16; ++i) {
;                 const int s = s0 + 16 * (i >> 3) + 8 * h + (i & 7);
;                 const unsigned u = __float_as_uint(idx[i] + 0.0f);
;                 const unsigned k = (u & 0x80000000u) ? ~u : (u | 0x80000000u);
;                 key[jt][i] = (s <= t0 + r) ? k : 0u;
;             }
;             if (hn) {
; #pragma unroll
;                 for (int ks = 0; ks < 4; ++ks) kf[ks] = kn[ks];
;             }
.Lkc_full_389:
	v_pk_add_f32 v[2:3], v[48:49], 0 op_sel_hi:[1,0]
	v_ashrrev_i32_e32 v4, 31, v2
	v_ashrrev_i32_e32 v5, 31, v3
	v_or_b32_e32 v4, 0x80000000, v4
	v_or_b32_e32 v5, 0x80000000, v5
	v_xor_b32_e32 v142, v2, v4
	v_xor_b32_e32 v141, v3, v5
	v_pk_add_f32 v[2:3], v[46:47], 0 op_sel_hi:[1,0]
	v_ashrrev_i32_e32 v4, 31, v2
	v_ashrrev_i32_e32 v5, 31, v3
	v_or_b32_e32 v4, 0x80000000, v4
	v_or_b32_e32 v5, 0x80000000, v5
	v_xor_b32_e32 v144, v2, v4
	v_xor_b32_e32 v143, v3, v5
	v_pk_add_f32 v[2:3], v[44:45], 0 op_sel_hi:[1,0]
	v_ashrrev_i32_e32 v4, 31, v2
	v_ashrrev_i32_e32 v5, 31, v3
	v_or_b32_e32 v4, 0x80000000, v4
	v_or_b32_e32 v5, 0x80000000, v5
	v_xor_b32_e32 v146, v2, v4
	v_xor_b32_e32 v145, v3, v5
	v_pk_add_f32 v[2:3], v[42:43], 0 op_sel_hi:[1,0]
	v_ashrrev_i32_e32 v4, 31, v2
	v_ashrrev_i32_e32 v5, 31, v3
	v_or_b32_e32 v4, 0x80000000, v4
	v_or_b32_e32 v5, 0x80000000, v5
	v_xor_b32_e32 v149, v2, v4
	v_xor_b32_e32 v147, v3, v5
	v_pk_add_f32 v[2:3], v[40:41], 0 op_sel_hi:[1,0]
	v_ashrrev_i32_e32 v4, 31, v2
	v_ashrrev_i32_e32 v5, 31, v3
	v_or_b32_e32 v4, 0x80000000, v4
	v_or_b32_e32 v5, 0x80000000, v5
	v_xor_b32_e32 v151, v2, v4
	v_xor_b32_e32 v150, v3, v5
	v_pk_add_f32 v[2:3], v[38:39], 0 op_sel_hi:[1,0]
	v_ashrrev_i32_e32 v4, 31, v2
	v_ashrrev_i32_e32 v5, 31, v3
	v_or_b32_e32 v4, 0x80000000, v4
	v_or_b32_e32 v5, 0x80000000, v5
	v_xor_b32_e32 v153, v2, v4
	v_xor_b32_e32 v152, v3, v5
	v_pk_add_f32 v[2:3], v[36:37], 0 op_sel_hi:[1,0]
	v_ashrrev_i32_e32 v4, 31, v2
	v_ashrrev_i32_e32 v5, 31, v3
	v_or_b32_e32 v4, 0x80000000, v4
	v_or_b32_e32 v5, 0x80000000, v5
	v_xor_b32_e32 v155, v2, v4
	v_xor_b32_e32 v154, v3, v5
	v_pk_add_f32 v[2:3], v[34:35], 0 op_sel_hi:[1,0]
	v_ashrrev_i32_e32 v4, 31, v2
	v_ashrrev_i32_e32 v5, 31, v3
	v_or_b32_e32 v4, 0x80000000, v4
	v_or_b32_e32 v5, 0x80000000, v5
	v_xor_b32_e32 v157, v2, v4
	v_xor_b32_e32 v156, v3, v5
.Lkc_done_389:
	v_mov_b64_e32 v[34:35], v[50:51]
	v_mov_b64_e32 v[38:39], v[54:55]
	v_mov_b64_e32 v[42:43], v[58:59]
	v_mov_b64_e32 v[46:47], v[62:63]
	s_and_b64 vcc, exec, vcc
	v_mov_b64_e32 v[36:37], v[52:53]
	v_mov_b64_e32 v[40:41], v[56:57]
	v_mov_b64_e32 v[44:45], v[60:61]
	v_mov_b64_e32 v[48:49], v[64:65]
	s_cbranch_vccz .LBB0_392
	s_waitcnt vmcnt(0)
	v_mov_b64_e32 v[36:37], v[20:21]
	v_mov_b64_e32 v[40:41], v[24:25]
	v_mov_b64_e32 v[44:45], v[28:29]
	v_mov_b64_e32 v[48:49], v[32:33]
	v_mov_b64_e32 v[34:35], v[18:19]
	v_mov_b64_e32 v[38:39], v[22:23]
	v_mov_b64_e32 v[42:43], v[26:27]
	v_mov_b64_e32 v[46:47], v[30:31]
.LBB0_392:
	v_readlane_b32 s6, v255, 40
	s_mov_b64 s[96:97], 0x2c0000
	v_readlane_b32 s88, v254, 41
	v_readlane_b32 s94, v254, 47
	v_readlane_b32 s95, v254, 48
	v_readlane_b32 s80, v254, 51
	v_readlane_b32 s86, v254, 39
	v_readlane_b32 s56, v254, 49
	v_readlane_b32 s81, v254, 52
	v_readlane_b32 s84, v254, 59
	v_readlane_b32 s94, v254, 61
	v_readlane_b32 s60, v254, 63
	v_readlane_b32 s76, v255, 15
	v_readlane_b32 s78, v255, 17
	v_readlane_b32 s58, v255, 33
	s_mov_b64 s[0:1], 0
	v_readlane_b32 s87, v254, 40
	v_readlane_b32 s89, v254, 42
	v_readlane_b32 s90, v254, 43
	v_readlane_b32 s91, v254, 44
	v_readlane_b32 s92, v254, 45
	v_readlane_b32 s93, v254, 46
	v_readlane_b32 s57, v254, 50
	v_readlane_b32 s85, v254, 60
	v_readlane_b32 s95, v254, 62
	v_readlane_b32 s61, v255, 0
	v_readlane_b32 s62, v255, 1
	v_readlane_b32 s63, v255, 2
	v_readlane_b32 s64, v255, 3
	v_readlane_b32 s65, v255, 4
	v_readlane_b32 s66, v255, 5
	v_readlane_b32 s67, v255, 6
	v_readlane_b32 s68, v255, 7
	v_readlane_b32 s69, v255, 8
	v_readlane_b32 s70, v255, 9
	v_readlane_b32 s71, v255, 10
	v_readlane_b32 s72, v255, 11
	v_readlane_b32 s73, v255, 12
	v_readlane_b32 s74, v255, 13
	v_readlane_b32 s75, v255, 14
	v_readlane_b32 s77, v255, 16
	v_readlane_b32 s79, v255, 18
	v_readlane_b32 s81, v254, 1
	s_mov_b64 s[82:83], 0x58000
	v_readlane_b32 s59, v255, 34
	v_readlane_b32 s7, v255, 41

; #define MFMA32(a, b, c) __builtin_amdgcn_mfma_f32_32x32x16_bf16((a), (b), (c), 0, 0, 0)
; DI void a1_task(unsigned char* shm, const bf16_t* prm, const bf16_t* prt, unsigned* mask, int b, int qt, const int tid) {
;     ...
;             for (int hh = 0; hh < 8; ++hh) {
;                 bf16x8 qa[4];
; #pragma unroll
;                 for (int ks = 0; ks < 4; ++ks) qa[ks] = *(const bf16x8*)(qb0 + hh * 128 + 32 * ks);
;                 const float wv = wqs[hh * 32 + r];
;                 asm volatile("s_waitcnt lgkmcnt(0)" ::: "memory");
;                 f32x16 acc;
; #pragma unroll
;                 for (int i = 0; i < 16; ++i) acc[i] = 0.f;
; #pragma unroll
;                 for (int ks = 0; ks < 4; ++ks) acc = MFMA32(kf[ks], qa[ks], acc);
; #pragma unroll
;                 for (int i = 0; i < 16; ++i) idx[i] = fmaf(wv, fmaxf(acc[i], 0.f), idx[i]);
;             }
; #pragma unroll
;             for (int i = 0; i < 16; ++i) {
;                 const int s = s0 + 16 * (i >> 3) + 8 * h + (i & 7);
;                 const unsigned u = __float_as_uint(idx[i] + 0.0f);
;                 const unsigned k = (u & 0x80000000u) ? ~u : (u | 0x80000000u);
;                 key[jt][i] = (s <= t0 + r) ? k : 0u;
;             }
.LBB0_399:
	v_add_u32_e32 v79, s1, v118
	ds_read_b128 v[2:5], v79
	ds_read_b128 v[66:69], v79 offset:32
	ds_read_b128 v[70:73], v79 offset:64
	ds_read_b128 v[74:77], v79 offset:96
	v_add_u32_e32 v80, s1, v135
	s_waitcnt lgkmcnt(3)
	v_mfma_f32_32x32x16_bf16 v[2:17], v[34:37], v[2:5], 0
	ds_read_b32 v78, v80
	s_waitcnt lgkmcnt(0)
	s_addk_i32 s1, 0x100
	s_cmpk_lg_i32 s1, 0x400
	s_waitcnt lgkmcnt(3)
	v_mfma_f32_32x32x16_bf16 v[2:17], v[38:41], v[66:69], v[2:17]
	s_waitcnt lgkmcnt(2)
	v_mfma_f32_32x32x16_bf16 v[2:17], v[42:45], v[70:73], v[2:17]
	s_waitcnt lgkmcnt(1)
	v_mfma_f32_32x32x16_bf16 v[2:17], v[46:49], v[74:77], v[2:17]
	s_nop 11
	v_max_f32_e32 v2, 0, v2
	v_max_f32_e32 v3, 0, v3
	s_waitcnt lgkmcnt(0)
	v_pk_fma_f32 v[64:65], v[78:79], v[2:3], v[64:65] op_sel_hi:[0,1,1]
	v_max_f32_e32 v2, 0, v4
	v_max_f32_e32 v3, 0, v5
	v_pk_fma_f32 v[62:63], v[78:79], v[2:3], v[62:63] op_sel_hi:[0,1,1]
	v_max_f32_e32 v2, 0, v6
	v_max_f32_e32 v3, 0, v7
	v_pk_fma_f32 v[60:61], v[78:79], v[2:3], v[60:61] op_sel_hi:[0,1,1]
	v_max_f32_e32 v2, 0, v8
	v_max_f32_e32 v3, 0, v9
	v_pk_fma_f32 v[58:59], v[78:79], v[2:3], v[58:59] op_sel_hi:[0,1,1]
	v_max_f32_e32 v2, 0, v10
	v_max_f32_e32 v3, 0, v11
	v_pk_fma_f32 v[56:57], v[78:79], v[2:3], v[56:57] op_sel_hi:[0,1,1]
	v_max_f32_e32 v2, 0, v12
	v_max_f32_e32 v3, 0, v13
	v_pk_fma_f32 v[54:55], v[78:79], v[2:3], v[54:55] op_sel_hi:[0,1,1]
	v_max_f32_e32 v2, 0, v14
	v_max_f32_e32 v3, 0, v15
	v_pk_fma_f32 v[52:53], v[78:79], v[2:3], v[52:53] op_sel_hi:[0,1,1]
	v_max_f32_e32 v2, 0, v16
	v_max_f32_e32 v3, 0, v17
	v_pk_fma_f32 v[50:51], v[78:79], v[2:3], v[50:51] op_sel_hi:[0,1,1]
	ds_read_b128 v[2:5], v79 offset:128
	ds_read_b128 v[66:69], v79 offset:160
	ds_read_b128 v[70:73], v79 offset:192
	ds_read_b128 v[74:77], v79 offset:224
	ds_read_b32 v78, v80 offset:128
	s_waitcnt lgkmcnt(4)
	v_mfma_f32_32x32x16_bf16 v[2:17], v[34:37], v[2:5], 0
	s_waitcnt lgkmcnt(0)
	s_waitcnt lgkmcnt(3)
	v_mfma_f32_32x32x16_bf16 v[2:17], v[38:41], v[66:69], v[2:17]
	s_waitcnt lgkmcnt(2)
	v_mfma_f32_32x32x16_bf16 v[2:17], v[42:45], v[70:73], v[2:17]
	s_waitcnt lgkmcnt(1)
	v_mfma_f32_32x32x16_bf16 v[2:17], v[46:49], v[74:77], v[2:17]
	s_nop 11
	v_max_f32_e32 v2, 0, v2
	v_max_f32_e32 v3, 0, v3
	s_waitcnt lgkmcnt(0)
	v_pk_fma_f32 v[64:65], v[78:79], v[2:3], v[64:65] op_sel_hi:[0,1,1]
	v_max_f32_e32 v2, 0, v4
	v_max_f32_e32 v3, 0, v5
	v_pk_fma_f32 v[62:63], v[78:79], v[2:3], v[62:63] op_sel_hi:[0,1,1]
	v_max_f32_e32 v2, 0, v6
	v_max_f32_e32 v3, 0, v7
	v_pk_fma_f32 v[60:61], v[78:79], v[2:3], v[60:61] op_sel_hi:[0,1,1]
	v_max_f32_e32 v2, 0, v8
	v_max_f32_e32 v3, 0, v9
	v_pk_fma_f32 v[58:59], v[78:79], v[2:3], v[58:59] op_sel_hi:[0,1,1]
	v_max_f32_e32 v2, 0, v10
	v_max_f32_e32 v3, 0, v11
	v_pk_fma_f32 v[56:57], v[78:79], v[2:3], v[56:57] op_sel_hi:[0,1,1]
	v_max_f32_e32 v2, 0, v12
	v_max_f32_e32 v3, 0, v13
	v_pk_fma_f32 v[54:55], v[78:79], v[2:3], v[54:55] op_sel_hi:[0,1,1]
	v_max_f32_e32 v2, 0, v14
	v_max_f32_e32 v3, 0, v15
	v_pk_fma_f32 v[52:53], v[78:79], v[2:3], v[52:53] op_sel_hi:[0,1,1]
	v_max_f32_e32 v2, 0, v16
	v_max_f32_e32 v3, 0, v17
	v_pk_fma_f32 v[50:51], v[78:79], v[2:3], v[50:51] op_sel_hi:[0,1,1]
	s_cbranch_scc1 .LBB0_399
	v_or_b32_e32 v8, s0, v98
	s_lshr_b32 s98, s0, 5
	s_cmp_lt_u32 s98, s2
	s_cbranch_scc1 .Lkc_full_399
	v_pk_add_f32 v[2:3], v[64:65], 0 op_sel_hi:[1,0]
	v_ashrrev_i32_e32 v4, 31, v2
	v_ashrrev_i32_e32 v5, 31, v3
	v_or_b32_e32 v4, 0x80000000, v4
	v_or_b32_e32 v5, 0x80000000, v5
	v_xor_b32_e32 v2, v2, v4
	v_xor_b32_e32 v3, v3, v5
	v_mov_b32_e32 v6, v8
	v_cmp_le_i32_e64 s[98:99], v6, v0
	v_or_b32_e32 v7, 1, v8
	s_nop 0
	v_cndmask_b32_e64 v166, 0, v2, s[98:99]
	v_cmp_le_i32_e64 s[98:99], v7, v0
	s_nop 1
	v_cndmask_b32_e64 v167, 0, v3, s[98:99]
	v_pk_add_f32 v[2:3], v[62:63], 0 op_sel_hi:[1,0]
	v_ashrrev_i32_e32 v4, 31, v2
	v_ashrrev_i32_e32 v5, 31, v3
	v_or_b32_e32 v4, 0x80000000, v4
	v_or_b32_e32 v5, 0x80000000, v5
	v_xor_b32_e32 v2, v2, v4
	v_xor_b32_e32 v3, v3, v5
	v_or_b32_e32 v6, 2, v8
	v_cmp_le_i32_e64 s[98:99], v6, v0
	v_or_b32_e32 v7, 3, v8
	s_nop 0
	v_cndmask_b32_e64 v159, 0, v2, s[98:99]
	v_cmp_le_i32_e64 s[98:99], v7, v0
	s_nop 1
	v_cndmask_b32_e64 v158, 0, v3, s[98:99]
	v_pk_add_f32 v[2:3], v[60:61], 0 op_sel_hi:[1,0]
	v_ashrrev_i32_e32 v4, 31, v2
	v_ashrrev_i32_e32 v5, 31, v3
	v_or_b32_e32 v4, 0x80000000, v4
	v_or_b32_e32 v5, 0x80000000, v5
	v_xor_b32_e32 v2, v2, v4
	v_xor_b32_e32 v3, v3, v5
	v_or_b32_e32 v6, 4, v8
	v_cmp_le_i32_e64 s[98:99], v6, v0
	v_or_b32_e32 v7, 5, v8
	s_nop 0
	v_cndmask_b32_e64 v161, 0, v2, s[98:99]
	v_cmp_le_i32_e64 s[98:99], v7, v0
	s_nop 1
	v_cndmask_b32_e64 v160, 0, v3, s[98:99]
	v_pk_add_f32 v[2:3], v[58:59], 0 op_sel_hi:[1,0]
	v_ashrrev_i32_e32 v4, 31, v2
	v_ashrrev_i32_e32 v5, 31, v3
	v_or_b32_e32 v4, 0x80000000, v4
	v_or_b32_e32 v5, 0x80000000, v5
	v_xor_b32_e32 v2, v2, v4
	v_xor_b32_e32 v3, v3, v5
	v_or_b32_e32 v6, 6, v8
	v_cmp_le_i32_e64 s[98:99], v6, v0
	v_or_b32_e32 v7, 7, v8
	s_nop 0
	v_cndmask_b32_e64 v163, 0, v2, s[98:99]
	v_cmp_le_i32_e64 s[98:99], v7, v0
	s_nop 1
	v_cndmask_b32_e64 v162, 0, v3, s[98:99]
	v_pk_add_f32 v[2:3], v[56:57], 0 op_sel_hi:[1,0]
	v_ashrrev_i32_e32 v4, 31, v2
	v_ashrrev_i32_e32 v5, 31, v3
	v_or_b32_e32 v4, 0x80000000, v4
	v_or_b32_e32 v5, 0x80000000, v5
	v_xor_b32_e32 v2, v2, v4
	v_xor_b32_e32 v3, v3, v5
	v_or_b32_e32 v6, 16, v8
	v_cmp_le_i32_e64 s[98:99], v6, v0
	v_or_b32_e32 v7, 17, v8
	s_nop 0
	v_cndmask_b32_e64 v165, 0, v2, s[98:99]
	v_cmp_le_i32_e64 s[98:99], v7, v0
	s_nop 1
	v_cndmask_b32_e64 v164, 0, v3, s[98:99]
	v_pk_add_f32 v[2:3], v[54:55], 0 op_sel_hi:[1,0]
	v_ashrrev_i32_e32 v4, 31, v2
	v_ashrrev_i32_e32 v5, 31, v3
	v_or_b32_e32 v4, 0x80000000, v4
	v_or_b32_e32 v5, 0x80000000, v5
	v_xor_b32_e32 v2, v2, v4
	v_xor_b32_e32 v3, v3, v5
	v_or_b32_e32 v6, 18, v8
	v_cmp_le_i32_e64 s[98:99], v6, v0
	v_or_b32_e32 v7, 19, v8
	s_nop 0
	v_cndmask_b32_e64 v169, 0, v2, s[98:99]
	v_cmp_le_i32_e64 s[98:99], v7, v0
	s_nop 1
	v_cndmask_b32_e64 v168, 0, v3, s[98:99]
	v_pk_add_f32 v[2:3], v[52:53], 0 op_sel_hi:[1,0]
	v_ashrrev_i32_e32 v4, 31, v2
	v_ashrrev_i32_e32 v5, 31, v3
	v_or_b32_e32 v4, 0x80000000, v4
	v_or_b32_e32 v5, 0x80000000, v5
	v_xor_b32_e32 v2, v2, v4
	v_xor_b32_e32 v3, v3, v5
	v_or_b32_e32 v6, 20, v8
	v_cmp_le_i32_e64 s[98:99], v6, v0
	v_or_b32_e32 v7, 21, v8
	s_nop 0
	v_cndmask_b32_e64 v171, 0, v2, s[98:99]
	v_cmp_le_i32_e64 s[98:99], v7, v0
	s_nop 1
	v_cndmask_b32_e64 v170, 0, v3, s[98:99]
	v_pk_add_f32 v[2:3], v[50:51], 0 op_sel_hi:[1,0]
	v_ashrrev_i32_e32 v4, 31, v2
	v_ashrrev_i32_e32 v5, 31, v3
	v_or_b32_e32 v4, 0x80000000, v4
	v_or_b32_e32 v5, 0x80000000, v5
	v_xor_b32_e32 v2, v2, v4
	v_xor_b32_e32 v3, v3, v5
	v_or_b32_e32 v6, 22, v8
	v_cmp_le_i32_e64 s[98:99], v6, v0
	v_or_b32_e32 v7, 23, v8
	s_nop 0
	v_cndmask_b32_e64 v173, 0, v2, s[98:99]
	v_cmp_le_i32_e64 s[98:99], v7, v0
	s_nop 1
	v_cndmask_b32_e64 v172, 0, v3, s[98:99]
	s_branch .Lkc_done_399
; DI void a1_task(unsigned char* shm, const bf16_t* prm, const bf16_t* prt, unsigned* mask, int b, int qt, const int tid) {
;     ...
;             for (int i = 0; i < 16; ++i) {
;                 const int s = s0 + 16 * (i >> 3) + 8 * h + (i & 7);
;                 const unsigned u = __float_as_uint(idx[i] + 0.0f);
;                 const unsigned k = (u & 0x80000000u) ? ~u : (u | 0x80000000u);
;                 key[jt][i] = (s <= t0 + r) ? k : 0u;
;             }
;             if (hn) {
; #pragma unroll
;                 for (int ks = 0; ks < 4; ++ks) kf[ks] = kn[ks];
;             }
.Lkc_full_399:
	v_pk_add_f32 v[2:3], v[64:65], 0 op_sel_hi:[1,0]
	v_ashrrev_i32_e32 v4, 31, v2
	v_ashrrev_i32_e32 v5, 31, v3
	v_or_b32_e32 v4, 0x80000000, v4
	v_or_b32_e32 v5, 0x80000000, v5
	v_xor_b32_e32 v166, v2, v4
	v_xor_b32_e32 v167, v3, v5
	v_pk_add_f32 v[2:3], v[62:63], 0 op_sel_hi:[1,0]
	v_ashrrev_i32_e32 v4, 31, v2
	v_ashrrev_i32_e32 v5, 31, v3
	v_or_b32_e32 v4, 0x80000000, v4
	v_or_b32_e32 v5, 0x80000000, v5
	v_xor_b32_e32 v159, v2, v4
	v_xor_b32_e32 v158, v3, v5
	v_pk_add_f32 v[2:3], v[60:61], 0 op_sel_hi:[1,0]
	v_ashrrev_i32_e32 v4, 31, v2
	v_ashrrev_i32_e32 v5, 31, v3
	v_or_b32_e32 v4, 0x80000000, v4
	v_or_b32_e32 v5, 0x80000000, v5
	v_xor_b32_e32 v161, v2, v4
	v_xor_b32_e32 v160, v3, v5
	v_pk_add_f32 v[2:3], v[58:59], 0 op_sel_hi:[1,0]
	v_ashrrev_i32_e32 v4, 31, v2
	v_ashrrev_i32_e32 v5, 31, v3
	v_or_b32_e32 v4, 0x80000000, v4
	v_or_b32_e32 v5, 0x80000000, v5
	v_xor_b32_e32 v163, v2, v4
	v_xor_b32_e32 v162, v3, v5
	v_pk_add_f32 v[2:3], v[56:57], 0 op_sel_hi:[1,0]
	v_ashrrev_i32_e32 v4, 31, v2
	v_ashrrev_i32_e32 v5, 31, v3
	v_or_b32_e32 v4, 0x80000000, v4
	v_or_b32_e32 v5, 0x80000000, v5
	v_xor_b32_e32 v165, v2, v4
	v_xor_b32_e32 v164, v3, v5
	v_pk_add_f32 v[2:3], v[54:55], 0 op_sel_hi:[1,0]
	v_ashrrev_i32_e32 v4, 31, v2
	v_ashrrev_i32_e32 v5, 31, v3
	v_or_b32_e32 v4, 0x80000000, v4
	v_or_b32_e32 v5, 0x80000000, v5
	v_xor_b32_e32 v169, v2, v4
	v_xor_b32_e32 v168, v3, v5
	v_pk_add_f32 v[2:3], v[52:53], 0 op_sel_hi:[1,0]
	v_ashrrev_i32_e32 v4, 31, v2
	v_ashrrev_i32_e32 v5, 31, v3
	v_or_b32_e32 v4, 0x80000000, v4
	v_or_b32_e32 v5, 0x80000000, v5
	v_xor_b32_e32 v171, v2, v4
	v_xor_b32_e32 v170, v3, v5
	v_pk_add_f32 v[2:3], v[50:51], 0 op_sel_hi:[1,0]
	v_ashrrev_i32_e32 v4, 31, v2
	v_ashrrev_i32_e32 v5, 31, v3
	v_or_b32_e32 v4, 0x80000000, v4
	v_or_b32_e32 v5, 0x80000000, v5
	v_xor_b32_e32 v173, v2, v4
	v_xor_b32_e32 v172, v3, v5
.Lkc_done_399:
	s_andn2_b64 vcc, exec, s[40:41]
	s_cbranch_vccnz .LBB0_402
	s_waitcnt vmcnt(0)
	v_mov_b64_e32 v[36:37], v[20:21]
	v_mov_b64_e32 v[40:41], v[24:25]
	v_mov_b64_e32 v[44:45], v[28:29]
	v_mov_b64_e32 v[48:49], v[32:33]
	v_mov_b64_e32 v[34:35], v[18:19]
	v_mov_b64_e32 v[38:39], v[22:23]
	v_mov_b64_e32 v[42:43], v[26:27]
	v_mov_b64_e32 v[46:47], v[30:31]
.LBB0_402:
	v_readlane_b32 s6, v255, 40
	s_mov_b64 s[96:97], 0x2c0000
	v_readlane_b32 s88, v254, 41
	v_readlane_b32 s94, v254, 47
	v_readlane_b32 s95, v254, 48
	v_readlane_b32 s80, v254, 51
	v_readlane_b32 s86, v254, 39
	v_readlane_b32 s56, v254, 49
	v_readlane_b32 s81, v254, 52
	v_readlane_b32 s84, v254, 59
	v_readlane_b32 s94, v254, 61
	v_readlane_b32 s60, v254, 63
	v_readlane_b32 s76, v255, 15
	v_readlane_b32 s78, v255, 17
	v_readlane_b32 s58, v255, 33
	v_readlane_b32 s87, v254, 40
	v_readlane_b32 s89, v254, 42
	v_readlane_b32 s90, v254, 43
	v_readlane_b32 s91, v254, 44
	v_readlane_b32 s92, v254, 45
	v_readlane_b32 s93, v254, 46
	v_readlane_b32 s57, v254, 50
	v_readlane_b32 s85, v254, 60
	v_readlane_b32 s95, v254, 62
	v_readlane_b32 s61, v255, 0
	v_readlane_b32 s62, v255, 1
	v_readlane_b32 s63, v255, 2
	v_readlane_b32 s64, v255, 3
	v_readlane_b32 s65, v255, 4
	v_readlane_b32 s66, v255, 5
	v_readlane_b32 s67, v255, 6
	v_readlane_b32 s68, v255, 7
	v_readlane_b32 s69, v255, 8
	v_readlane_b32 s70, v255, 9
	v_readlane_b32 s71, v255, 10
	v_readlane_b32 s72, v255, 11
	v_readlane_b32 s73, v255, 12
	v_readlane_b32 s74, v255, 13
	v_readlane_b32 s75, v255, 14
	v_readlane_b32 s77, v255, 16
	v_readlane_b32 s79, v255, 18
	v_readlane_b32 s81, v254, 1
	s_mov_b64 s[82:83], 0x58000
	v_readlane_b32 s59, v255, 34
	v_readlane_b32 s7, v255, 41
	s_branch .LBB0_404

; #define MFMA32(a, b, c) __builtin_amdgcn_mfma_f32_32x32x16_bf16((a), (b), (c), 0, 0, 0)
; DI void a1_task(unsigned char* shm, const bf16_t* prm, const bf16_t* prt, unsigned* mask, int b, int qt, const int tid) {
;     ...
;             for (int hh = 0; hh < 8; ++hh) {
;                 bf16x8 qa[4];
; #pragma unroll
;                 for (int ks = 0; ks < 4; ++ks) qa[ks] = *(const bf16x8*)(qb0 + hh * 128 + 32 * ks);
;                 const float wv = wqs[hh * 32 + r];
;                 asm volatile("s_waitcnt lgkmcnt(0)" ::: "memory");
;                 f32x16 acc;
; #pragma unroll
;                 for (int i = 0; i < 16; ++i) acc[i] = 0.f;
; #pragma unroll
;                 for (int ks = 0; ks < 4; ++ks) acc = MFMA32(kf[ks], qa[ks], acc);
; #pragma unroll
;                 for (int i = 0; i < 16; ++i) idx[i] = fmaf(wv, fmaxf(acc[i], 0.f), idx[i]);
;             }
; #pragma unroll
;             for (int i = 0; i < 16; ++i) {
;                 const int s = s0 + 16 * (i >> 3) + 8 * h + (i & 7);
;                 const unsigned u = __float_as_uint(idx[i] + 0.0f);
;                 const unsigned k = (u & 0x80000000u) ? ~u : (u | 0x80000000u);
;                 key[jt][i] = (s <= t0 + r) ? k : 0u;
;             }
.LBB0_408:
	v_add_u32_e32 v95, s1, v118
	ds_read_b128 v[2:5], v95
	ds_read_b128 v[82:85], v95 offset:32
	ds_read_b128 v[86:89], v95 offset:64
	ds_read_b128 v[90:93], v95 offset:96
	v_add_u32_e32 v96, s1, v135
	s_waitcnt lgkmcnt(3)
	v_mfma_f32_32x32x16_bf16 v[2:17], v[34:37], v[2:5], 0
	ds_read_b32 v94, v96
	s_waitcnt lgkmcnt(0)
	s_addk_i32 s1, 0x100
	s_cmpk_lg_i32 s1, 0x400
	s_waitcnt lgkmcnt(3)
	v_mfma_f32_32x32x16_bf16 v[2:17], v[38:41], v[82:85], v[2:17]
	s_waitcnt lgkmcnt(2)
	v_mfma_f32_32x32x16_bf16 v[2:17], v[42:45], v[86:89], v[2:17]
	s_waitcnt lgkmcnt(1)
	v_mfma_f32_32x32x16_bf16 v[2:17], v[46:49], v[90:93], v[2:17]
	s_nop 11
	v_max_f32_e32 v2, 0, v2
	v_max_f32_e32 v3, 0, v3
	s_waitcnt lgkmcnt(0)
	v_pk_fma_f32 v[80:81], v[94:95], v[2:3], v[80:81] op_sel_hi:[0,1,1]
	v_max_f32_e32 v2, 0, v4
	v_max_f32_e32 v3, 0, v5
	v_pk_fma_f32 v[78:79], v[94:95], v[2:3], v[78:79] op_sel_hi:[0,1,1]
	v_max_f32_e32 v2, 0, v6
	v_max_f32_e32 v3, 0, v7
	v_pk_fma_f32 v[76:77], v[94:95], v[2:3], v[76:77] op_sel_hi:[0,1,1]
	v_max_f32_e32 v2, 0, v8
	v_max_f32_e32 v3, 0, v9
	v_pk_fma_f32 v[74:75], v[94:95], v[2:3], v[74:75] op_sel_hi:[0,1,1]
	v_max_f32_e32 v2, 0, v10
	v_max_f32_e32 v3, 0, v11
	v_pk_fma_f32 v[72:73], v[94:95], v[2:3], v[72:73] op_sel_hi:[0,1,1]
	v_max_f32_e32 v2, 0, v12
	v_max_f32_e32 v3, 0, v13
	v_pk_fma_f32 v[70:71], v[94:95], v[2:3], v[70:71] op_sel_hi:[0,1,1]
	v_max_f32_e32 v2, 0, v14
	v_max_f32_e32 v3, 0, v15
	v_pk_fma_f32 v[68:69], v[94:95], v[2:3], v[68:69] op_sel_hi:[0,1,1]
	v_max_f32_e32 v2, 0, v16
	v_max_f32_e32 v3, 0, v17
	v_pk_fma_f32 v[66:67], v[94:95], v[2:3], v[66:67] op_sel_hi:[0,1,1]
	ds_read_b128 v[2:5], v95 offset:128
	ds_read_b128 v[82:85], v95 offset:160
	ds_read_b128 v[86:89], v95 offset:192
	ds_read_b128 v[90:93], v95 offset:224
	ds_read_b32 v94, v96 offset:128
	s_waitcnt lgkmcnt(4)
	v_mfma_f32_32x32x16_bf16 v[2:17], v[34:37], v[2:5], 0
	s_waitcnt lgkmcnt(0)
	s_waitcnt lgkmcnt(3)
	v_mfma_f32_32x32x16_bf16 v[2:17], v[38:41], v[82:85], v[2:17]
	s_waitcnt lgkmcnt(2)
	v_mfma_f32_32x32x16_bf16 v[2:17], v[42:45], v[86:89], v[2:17]
	s_waitcnt lgkmcnt(1)
	v_mfma_f32_32x32x16_bf16 v[2:17], v[46:49], v[90:93], v[2:17]
	s_nop 11
	v_max_f32_e32 v2, 0, v2
	v_max_f32_e32 v3, 0, v3
	s_waitcnt lgkmcnt(0)
	v_pk_fma_f32 v[80:81], v[94:95], v[2:3], v[80:81] op_sel_hi:[0,1,1]
	v_max_f32_e32 v2, 0, v4
	v_max_f32_e32 v3, 0, v5
	v_pk_fma_f32 v[78:79], v[94:95], v[2:3], v[78:79] op_sel_hi:[0,1,1]
	v_max_f32_e32 v2, 0, v6
	v_max_f32_e32 v3, 0, v7
	v_pk_fma_f32 v[76:77], v[94:95], v[2:3], v[76:77] op_sel_hi:[0,1,1]
	v_max_f32_e32 v2, 0, v8
	v_max_f32_e32 v3, 0, v9
	v_pk_fma_f32 v[74:75], v[94:95], v[2:3], v[74:75] op_sel_hi:[0,1,1]
	v_max_f32_e32 v2, 0, v10
	v_max_f32_e32 v3, 0, v11
	v_pk_fma_f32 v[72:73], v[94:95], v[2:3], v[72:73] op_sel_hi:[0,1,1]
	v_max_f32_e32 v2, 0, v12
	v_max_f32_e32 v3, 0, v13
	v_pk_fma_f32 v[70:71], v[94:95], v[2:3], v[70:71] op_sel_hi:[0,1,1]
	v_max_f32_e32 v2, 0, v14
	v_max_f32_e32 v3, 0, v15
	v_pk_fma_f32 v[68:69], v[94:95], v[2:3], v[68:69] op_sel_hi:[0,1,1]
	v_max_f32_e32 v2, 0, v16
	v_max_f32_e32 v3, 0, v17
	v_pk_fma_f32 v[66:67], v[94:95], v[2:3], v[66:67] op_sel_hi:[0,1,1]
	s_cbranch_scc1 .LBB0_408
	v_or_b32_e32 v8, s0, v98
	s_lshr_b32 s98, s0, 5
	s_cmp_lt_u32 s98, s2
	s_cbranch_scc1 .Lkc_full_408
	v_pk_add_f32 v[2:3], v[80:81], 0 op_sel_hi:[1,0]
	v_ashrrev_i32_e32 v4, 31, v2
	v_ashrrev_i32_e32 v5, 31, v3
	v_or_b32_e32 v4, 0x80000000, v4
	v_or_b32_e32 v5, 0x80000000, v5
	v_xor_b32_e32 v2, v2, v4
	v_xor_b32_e32 v3, v3, v5
	v_mov_b32_e32 v6, v8
	v_cmp_le_i32_e64 s[98:99], v6, v0
	v_or_b32_e32 v7, 1, v8
	s_nop 0
	v_cndmask_b32_e64 v175, 0, v2, s[98:99]
	v_cmp_le_i32_e64 s[98:99], v7, v0
	s_nop 1
	v_cndmask_b32_e64 v174, 0, v3, s[98:99]
	v_pk_add_f32 v[2:3], v[78:79], 0 op_sel_hi:[1,0]
	v_ashrrev_i32_e32 v4, 31, v2
	v_ashrrev_i32_e32 v5, 31, v3
	v_or_b32_e32 v4, 0x80000000, v4
	v_or_b32_e32 v5, 0x80000000, v5
	v_xor_b32_e32 v2, v2, v4
	v_xor_b32_e32 v3, v3, v5
	v_or_b32_e32 v6, 2, v8
	v_cmp_le_i32_e64 s[98:99], v6, v0
	v_or_b32_e32 v7, 3, v8
	s_nop 0
	v_cndmask_b32_e64 v177, 0, v2, s[98:99]
	v_cmp_le_i32_e64 s[98:99], v7, v0
	s_nop 1
	v_cndmask_b32_e64 v176, 0, v3, s[98:99]
	v_pk_add_f32 v[2:3], v[76:77], 0 op_sel_hi:[1,0]
	v_ashrrev_i32_e32 v4, 31, v2
	v_ashrrev_i32_e32 v5, 31, v3
	v_or_b32_e32 v4, 0x80000000, v4
	v_or_b32_e32 v5, 0x80000000, v5
	v_xor_b32_e32 v2, v2, v4
	v_xor_b32_e32 v3, v3, v5
	v_or_b32_e32 v6, 4, v8
	v_cmp_le_i32_e64 s[98:99], v6, v0
	v_or_b32_e32 v7, 5, v8
	s_nop 0
	v_cndmask_b32_e64 v179, 0, v2, s[98:99]
	v_cmp_le_i32_e64 s[98:99], v7, v0
	s_nop 1
	v_cndmask_b32_e64 v178, 0, v3, s[98:99]
	v_pk_add_f32 v[2:3], v[74:75], 0 op_sel_hi:[1,0]
	v_ashrrev_i32_e32 v4, 31, v2
	v_ashrrev_i32_e32 v5, 31, v3
	v_or_b32_e32 v4, 0x80000000, v4
	v_or_b32_e32 v5, 0x80000000, v5
	v_xor_b32_e32 v2, v2, v4
	v_xor_b32_e32 v3, v3, v5
	v_or_b32_e32 v6, 6, v8
	v_cmp_le_i32_e64 s[98:99], v6, v0
	v_or_b32_e32 v7, 7, v8
	s_nop 0
	v_cndmask_b32_e64 v181, 0, v2, s[98:99]
	v_cmp_le_i32_e64 s[98:99], v7, v0
	s_nop 1
	v_cndmask_b32_e64 v180, 0, v3, s[98:99]
	v_pk_add_f32 v[2:3], v[72:73], 0 op_sel_hi:[1,0]
	v_ashrrev_i32_e32 v4, 31, v2
	v_ashrrev_i32_e32 v5, 31, v3
	v_or_b32_e32 v4, 0x80000000, v4
	v_or_b32_e32 v5, 0x80000000, v5
	v_xor_b32_e32 v2, v2, v4
	v_xor_b32_e32 v3, v3, v5
	v_or_b32_e32 v6, 16, v8
	v_cmp_le_i32_e64 s[98:99], v6, v0
	v_or_b32_e32 v7, 17, v8
	s_nop 0
	v_cndmask_b32_e64 v183, 0, v2, s[98:99]
	v_cmp_le_i32_e64 s[98:99], v7, v0
	s_nop 1
	v_cndmask_b32_e64 v182, 0, v3, s[98:99]
	v_pk_add_f32 v[2:3], v[70:71], 0 op_sel_hi:[1,0]
	v_ashrrev_i32_e32 v4, 31, v2
	v_ashrrev_i32_e32 v5, 31, v3
	v_or_b32_e32 v4, 0x80000000, v4
	v_or_b32_e32 v5, 0x80000000, v5
	v_xor_b32_e32 v2, v2, v4
	v_xor_b32_e32 v3, v3, v5
	v_or_b32_e32 v6, 18, v8
	v_cmp_le_i32_e64 s[98:99], v6, v0
	v_or_b32_e32 v7, 19, v8
	s_nop 0
	v_cndmask_b32_e64 v185, 0, v2, s[98:99]
	v_cmp_le_i32_e64 s[98:99], v7, v0
	s_nop 1
	v_cndmask_b32_e64 v184, 0, v3, s[98:99]
	v_pk_add_f32 v[2:3], v[68:69], 0 op_sel_hi:[1,0]
	v_ashrrev_i32_e32 v4, 31, v2
	v_ashrrev_i32_e32 v5, 31, v3
	v_or_b32_e32 v4, 0x80000000, v4
	v_or_b32_e32 v5, 0x80000000, v5
	v_xor_b32_e32 v2, v2, v4
	v_xor_b32_e32 v3, v3, v5
	v_or_b32_e32 v6, 20, v8
	v_cmp_le_i32_e64 s[98:99], v6, v0
	v_or_b32_e32 v7, 21, v8
	s_nop 0
	v_cndmask_b32_e64 v187, 0, v2, s[98:99]
	v_cmp_le_i32_e64 s[98:99], v7, v0
	s_nop 1
	v_cndmask_b32_e64 v186, 0, v3, s[98:99]
	v_pk_add_f32 v[2:3], v[66:67], 0 op_sel_hi:[1,0]
	v_ashrrev_i32_e32 v4, 31, v2
	v_ashrrev_i32_e32 v5, 31, v3
	v_or_b32_e32 v4, 0x80000000, v4
	v_or_b32_e32 v5, 0x80000000, v5
	v_xor_b32_e32 v2, v2, v4
	v_xor_b32_e32 v3, v3, v5
	v_or_b32_e32 v6, 22, v8
	v_cmp_le_i32_e64 s[98:99], v6, v0
	v_or_b32_e32 v7, 23, v8
	s_nop 0
	v_cndmask_b32_e64 v189, 0, v2, s[98:99]
	v_cmp_le_i32_e64 s[98:99], v7, v0
	s_nop 1
	v_cndmask_b32_e64 v188, 0, v3, s[98:99]
	s_branch .Lkc_done_408
; DI void a1_task(unsigned char* shm, const bf16_t* prm, const bf16_t* prt, unsigned* mask, int b, int qt, const int tid) {
;     ...
;             for (int i = 0; i < 16; ++i) {
;                 const int s = s0 + 16 * (i >> 3) + 8 * h + (i & 7);
;                 const unsigned u = __float_as_uint(idx[i] + 0.0f);
;                 const unsigned k = (u & 0x80000000u) ? ~u : (u | 0x80000000u);
;                 key[jt][i] = (s <= t0 + r) ? k : 0u;
;             }
;             if (hn) {
; #pragma unroll
;                 for (int ks = 0; ks < 4; ++ks) kf[ks] = kn[ks];
;             }
.Lkc_full_408:
	v_pk_add_f32 v[2:3], v[80:81], 0 op_sel_hi:[1,0]
	v_ashrrev_i32_e32 v4, 31, v2
	v_ashrrev_i32_e32 v5, 31, v3
	v_or_b32_e32 v4, 0x80000000, v4
	v_or_b32_e32 v5, 0x80000000, v5
	v_xor_b32_e32 v175, v2, v4
	v_xor_b32_e32 v174, v3, v5
	v_pk_add_f32 v[2:3], v[78:79], 0 op_sel_hi:[1,0]
	v_ashrrev_i32_e32 v4, 31, v2
	v_ashrrev_i32_e32 v5, 31, v3
	v_or_b32_e32 v4, 0x80000000, v4
	v_or_b32_e32 v5, 0x80000000, v5
	v_xor_b32_e32 v177, v2, v4
	v_xor_b32_e32 v176, v3, v5
	v_pk_add_f32 v[2:3], v[76:77], 0 op_sel_hi:[1,0]
	v_ashrrev_i32_e32 v4, 31, v2
	v_ashrrev_i32_e32 v5, 31, v3
	v_or_b32_e32 v4, 0x80000000, v4
	v_or_b32_e32 v5, 0x80000000, v5
	v_xor_b32_e32 v179, v2, v4
	v_xor_b32_e32 v178, v3, v5
	v_pk_add_f32 v[2:3], v[74:75], 0 op_sel_hi:[1,0]
	v_ashrrev_i32_e32 v4, 31, v2
	v_ashrrev_i32_e32 v5, 31, v3
	v_or_b32_e32 v4, 0x80000000, v4
	v_or_b32_e32 v5, 0x80000000, v5
	v_xor_b32_e32 v181, v2, v4
	v_xor_b32_e32 v180, v3, v5
	v_pk_add_f32 v[2:3], v[72:73], 0 op_sel_hi:[1,0]
	v_ashrrev_i32_e32 v4, 31, v2
	v_ashrrev_i32_e32 v5, 31, v3
	v_or_b32_e32 v4, 0x80000000, v4
	v_or_b32_e32 v5, 0x80000000, v5
	v_xor_b32_e32 v183, v2, v4
	v_xor_b32_e32 v182, v3, v5
	v_pk_add_f32 v[2:3], v[70:71], 0 op_sel_hi:[1,0]
	v_ashrrev_i32_e32 v4, 31, v2
	v_ashrrev_i32_e32 v5, 31, v3
	v_or_b32_e32 v4, 0x80000000, v4
	v_or_b32_e32 v5, 0x80000000, v5
	v_xor_b32_e32 v185, v2, v4
	v_xor_b32_e32 v184, v3, v5
	v_pk_add_f32 v[2:3], v[68:69], 0 op_sel_hi:[1,0]
	v_ashrrev_i32_e32 v4, 31, v2
	v_ashrrev_i32_e32 v5, 31, v3
	v_or_b32_e32 v4, 0x80000000, v4
	v_or_b32_e32 v5, 0x80000000, v5
	v_xor_b32_e32 v187, v2, v4
	v_xor_b32_e32 v186, v3, v5
	v_pk_add_f32 v[2:3], v[66:67], 0 op_sel_hi:[1,0]
	v_ashrrev_i32_e32 v4, 31, v2
	v_ashrrev_i32_e32 v5, 31, v3
	v_or_b32_e32 v4, 0x80000000, v4
	v_or_b32_e32 v5, 0x80000000, v5
	v_xor_b32_e32 v189, v2, v4
	v_xor_b32_e32 v188, v3, v5
.Lkc_done_408:
	v_mov_b64_e32 v[68:69], v[36:37]
	v_mov_b64_e32 v[76:77], v[40:41]
	v_mov_b64_e32 v[84:85], v[44:45]
	v_mov_b64_e32 v[92:93], v[48:49]
	s_andn2_b64 vcc, exec, s[40:41]
	v_mov_b64_e32 v[66:67], v[34:35]
	v_mov_b64_e32 v[74:75], v[38:39]
	v_mov_b64_e32 v[82:83], v[42:43]
	v_mov_b64_e32 v[90:91], v[46:47]
	s_cbranch_vccnz .LBB0_411
	s_waitcnt vmcnt(3)
	v_mov_b64_e32 v[68:69], v[52:53]
	s_waitcnt vmcnt(2)
	v_mov_b64_e32 v[76:77], v[56:57]
	s_waitcnt vmcnt(1)
	v_mov_b64_e32 v[84:85], v[60:61]
	s_waitcnt vmcnt(0)
	v_mov_b64_e32 v[92:93], v[64:65]
	v_mov_b64_e32 v[66:67], v[50:51]
	v_mov_b64_e32 v[74:75], v[54:55]
	v_mov_b64_e32 v[82:83], v[58:59]
	v_mov_b64_e32 v[90:91], v[62:63]
.LBB0_411:
	s_mov_b64 s[96:97], 0x2c0000
	v_readlane_b32 s6, v255, 40
	v_readlane_b32 s88, v254, 41
	v_readlane_b32 s94, v254, 47
	v_readlane_b32 s95, v254, 48
	v_readlane_b32 s80, v254, 51
	v_readlane_b32 s86, v254, 39
	v_readlane_b32 s56, v254, 49
	v_readlane_b32 s81, v254, 52
	v_readlane_b32 s84, v254, 59
	v_readlane_b32 s94, v254, 61
	v_readlane_b32 s60, v254, 63
	v_readlane_b32 s76, v255, 15
	v_readlane_b32 s78, v255, 17
	v_readlane_b32 s58, v255, 33
	s_mov_b64 s[0:1], 0
	v_readlane_b32 s87, v254, 40
	v_readlane_b32 s89, v254, 42
	v_readlane_b32 s90, v254, 43
	v_readlane_b32 s91, v254, 44
	v_readlane_b32 s92, v254, 45
	v_readlane_b32 s93, v254, 46
	v_readlane_b32 s57, v254, 50
	v_readlane_b32 s85, v254, 60
	v_readlane_b32 s95, v254, 62
	v_readlane_b32 s61, v255, 0
	v_readlane_b32 s62, v255, 1
	v_readlane_b32 s63, v255, 2
	v_readlane_b32 s64, v255, 3
	v_readlane_b32 s65, v255, 4
	v_readlane_b32 s66, v255, 5
	v_readlane_b32 s67, v255, 6
	v_readlane_b32 s68, v255, 7
	v_readlane_b32 s69, v255, 8
	v_readlane_b32 s70, v255, 9
	v_readlane_b32 s71, v255, 10
	v_readlane_b32 s72, v255, 11
	v_readlane_b32 s73, v255, 12
	v_readlane_b32 s74, v255, 13
	v_readlane_b32 s75, v255, 14
	v_readlane_b32 s77, v255, 16
	v_readlane_b32 s79, v255, 18
	v_readlane_b32 s81, v254, 1
	s_mov_b64 s[82:83], 0x58000
	v_readlane_b32 s59, v255, 34
	v_readlane_b32 s7, v255, 41

; #define MFMA32(a, b, c) __builtin_amdgcn_mfma_f32_32x32x16_bf16((a), (b), (c), 0, 0, 0)
; DI void a1_task(unsigned char* shm, const bf16_t* prm, const bf16_t* prt, unsigned* mask, int b, int qt, const int tid) {
;     ...
;             for (int hh = 0; hh < 8; ++hh) {
;                 bf16x8 qa[4];
; #pragma unroll
;                 for (int ks = 0; ks < 4; ++ks) qa[ks] = *(const bf16x8*)(qb0 + hh * 128 + 32 * ks);
;                 const float wv = wqs[hh * 32 + r];
;                 asm volatile("s_waitcnt lgkmcnt(0)" ::: "memory");
;                 f32x16 acc;
; #pragma unroll
;                 for (int i = 0; i < 16; ++i) acc[i] = 0.f;
; #pragma unroll
;                 for (int ks = 0; ks < 4; ++ks) acc = MFMA32(kf[ks], qa[ks], acc);
; #pragma unroll
;                 for (int i = 0; i < 16; ++i) idx[i] = fmaf(wv, fmaxf(acc[i], 0.f), idx[i]);
;             }
; #pragma unroll
;             for (int i = 0; i < 16; ++i) {
;                 const int s = s0 + 16 * (i >> 3) + 8 * h + (i & 7);
;                 const unsigned u = __float_as_uint(idx[i] + 0.0f);
;                 const unsigned k = (u & 0x80000000u) ? ~u : (u | 0x80000000u);
;                 key[jt][i] = (s <= t0 + r) ? k : 0u;
;             }
.LBB0_418:
	v_add_u32_e32 v95, s1, v118
	ds_read_b128 v[2:5], v95
	ds_read_b128 v[70:73], v95 offset:32
	ds_read_b128 v[78:81], v95 offset:64
	ds_read_b128 v[86:89], v95 offset:96
	v_add_u32_e32 v96, s1, v135
	s_waitcnt lgkmcnt(3)
	v_mfma_f32_32x32x16_bf16 v[2:17], v[66:69], v[2:5], 0
	ds_read_b32 v94, v96
	s_waitcnt lgkmcnt(0)
	s_addk_i32 s1, 0x100
	s_cmpk_lg_i32 s1, 0x400
	s_waitcnt lgkmcnt(3)
	v_mfma_f32_32x32x16_bf16 v[2:17], v[74:77], v[70:73], v[2:17]
	s_waitcnt lgkmcnt(2)
	v_mfma_f32_32x32x16_bf16 v[2:17], v[82:85], v[78:81], v[2:17]
	s_waitcnt lgkmcnt(1)
	v_mfma_f32_32x32x16_bf16 v[2:17], v[90:93], v[86:89], v[2:17]
	s_nop 11
	v_max_f32_e32 v2, 0, v2
	v_max_f32_e32 v3, 0, v3
	s_waitcnt lgkmcnt(0)
	v_pk_fma_f32 v[32:33], v[94:95], v[2:3], v[32:33] op_sel_hi:[0,1,1]
	v_max_f32_e32 v2, 0, v4
	v_max_f32_e32 v3, 0, v5
	v_pk_fma_f32 v[30:31], v[94:95], v[2:3], v[30:31] op_sel_hi:[0,1,1]
	v_max_f32_e32 v2, 0, v6
	v_max_f32_e32 v3, 0, v7
	v_pk_fma_f32 v[28:29], v[94:95], v[2:3], v[28:29] op_sel_hi:[0,1,1]
	v_max_f32_e32 v2, 0, v8
	v_max_f32_e32 v3, 0, v9
	v_pk_fma_f32 v[26:27], v[94:95], v[2:3], v[26:27] op_sel_hi:[0,1,1]
	v_max_f32_e32 v2, 0, v10
	v_max_f32_e32 v3, 0, v11
	v_pk_fma_f32 v[24:25], v[94:95], v[2:3], v[24:25] op_sel_hi:[0,1,1]
	v_max_f32_e32 v2, 0, v12
	v_max_f32_e32 v3, 0, v13
	v_pk_fma_f32 v[22:23], v[94:95], v[2:3], v[22:23] op_sel_hi:[0,1,1]
	v_max_f32_e32 v2, 0, v14
	v_max_f32_e32 v3, 0, v15
	v_pk_fma_f32 v[20:21], v[94:95], v[2:3], v[20:21] op_sel_hi:[0,1,1]
	v_max_f32_e32 v2, 0, v16
	v_max_f32_e32 v3, 0, v17
	v_pk_fma_f32 v[18:19], v[94:95], v[2:3], v[18:19] op_sel_hi:[0,1,1]
	ds_read_b128 v[2:5], v95 offset:128
	ds_read_b128 v[70:73], v95 offset:160
	ds_read_b128 v[78:81], v95 offset:192
	ds_read_b128 v[86:89], v95 offset:224
	ds_read_b32 v94, v96 offset:128
	s_waitcnt lgkmcnt(4)
	v_mfma_f32_32x32x16_bf16 v[2:17], v[66:69], v[2:5], 0
	s_waitcnt lgkmcnt(0)
	s_waitcnt lgkmcnt(3)
	v_mfma_f32_32x32x16_bf16 v[2:17], v[74:77], v[70:73], v[2:17]
	s_waitcnt lgkmcnt(2)
	v_mfma_f32_32x32x16_bf16 v[2:17], v[82:85], v[78:81], v[2:17]
	s_waitcnt lgkmcnt(1)
	v_mfma_f32_32x32x16_bf16 v[2:17], v[90:93], v[86:89], v[2:17]
	s_nop 11
	v_max_f32_e32 v2, 0, v2
	v_max_f32_e32 v3, 0, v3
	s_waitcnt lgkmcnt(0)
	v_pk_fma_f32 v[32:33], v[94:95], v[2:3], v[32:33] op_sel_hi:[0,1,1]
	v_max_f32_e32 v2, 0, v4
	v_max_f32_e32 v3, 0, v5
	v_pk_fma_f32 v[30:31], v[94:95], v[2:3], v[30:31] op_sel_hi:[0,1,1]
	v_max_f32_e32 v2, 0, v6
	v_max_f32_e32 v3, 0, v7
	v_pk_fma_f32 v[28:29], v[94:95], v[2:3], v[28:29] op_sel_hi:[0,1,1]
	v_max_f32_e32 v2, 0, v8
	v_max_f32_e32 v3, 0, v9
	v_pk_fma_f32 v[26:27], v[94:95], v[2:3], v[26:27] op_sel_hi:[0,1,1]
	v_max_f32_e32 v2, 0, v10
	v_max_f32_e32 v3, 0, v11
	v_pk_fma_f32 v[24:25], v[94:95], v[2:3], v[24:25] op_sel_hi:[0,1,1]
	v_max_f32_e32 v2, 0, v12
	v_max_f32_e32 v3, 0, v13
	v_pk_fma_f32 v[22:23], v[94:95], v[2:3], v[22:23] op_sel_hi:[0,1,1]
	v_max_f32_e32 v2, 0, v14
	v_max_f32_e32 v3, 0, v15
	v_pk_fma_f32 v[20:21], v[94:95], v[2:3], v[20:21] op_sel_hi:[0,1,1]
	v_max_f32_e32 v2, 0, v16
	v_max_f32_e32 v3, 0, v17
	v_pk_fma_f32 v[18:19], v[94:95], v[2:3], v[18:19] op_sel_hi:[0,1,1]
	s_cbranch_scc1 .LBB0_418
	v_or_b32_e32 v8, s0, v98
	s_lshr_b32 s98, s0, 5
	s_cmp_lt_u32 s98, s2
	s_cbranch_scc1 .Lkc_full_418
	v_pk_add_f32 v[2:3], v[32:33], 0 op_sel_hi:[1,0]
	v_ashrrev_i32_e32 v4, 31, v2
	v_ashrrev_i32_e32 v5, 31, v3
	v_or_b32_e32 v4, 0x80000000, v4
	v_or_b32_e32 v5, 0x80000000, v5
	v_xor_b32_e32 v2, v2, v4
	v_xor_b32_e32 v3, v3, v5
	v_mov_b32_e32 v6, v8
	v_cmp_le_i32_e64 s[98:99], v6, v0
	v_or_b32_e32 v7, 1, v8
	s_nop 0
	v_cndmask_b32_e64 v191, 0, v2, s[98:99]
	v_cmp_le_i32_e64 s[98:99], v7, v0
	s_nop 1
	v_cndmask_b32_e64 v190, 0, v3, s[98:99]
	v_pk_add_f32 v[2:3], v[30:31], 0 op_sel_hi:[1,0]
	v_ashrrev_i32_e32 v4, 31, v2
	v_ashrrev_i32_e32 v5, 31, v3
	v_or_b32_e32 v4, 0x80000000, v4
	v_or_b32_e32 v5, 0x80000000, v5
	v_xor_b32_e32 v2, v2, v4
	v_xor_b32_e32 v3, v3, v5
	v_or_b32_e32 v6, 2, v8
	v_cmp_le_i32_e64 s[98:99], v6, v0
	v_or_b32_e32 v7, 3, v8
	s_nop 0
	v_cndmask_b32_e64 v193, 0, v2, s[98:99]
	v_cmp_le_i32_e64 s[98:99], v7, v0
	s_nop 1
	v_cndmask_b32_e64 v192, 0, v3, s[98:99]
	v_pk_add_f32 v[2:3], v[28:29], 0 op_sel_hi:[1,0]
	v_ashrrev_i32_e32 v4, 31, v2
	v_ashrrev_i32_e32 v5, 31, v3
	v_or_b32_e32 v4, 0x80000000, v4
	v_or_b32_e32 v5, 0x80000000, v5
	v_xor_b32_e32 v2, v2, v4
	v_xor_b32_e32 v3, v3, v5
	v_or_b32_e32 v6, 4, v8
	v_cmp_le_i32_e64 s[98:99], v6, v0
	v_or_b32_e32 v7, 5, v8
	s_nop 0
	v_cndmask_b32_e64 v212, 0, v2, s[98:99]
	v_cmp_le_i32_e64 s[98:99], v7, v0
	s_nop 1
	v_cndmask_b32_e64 v211, 0, v3, s[98:99]
	v_pk_add_f32 v[2:3], v[26:27], 0 op_sel_hi:[1,0]
	v_ashrrev_i32_e32 v4, 31, v2
	v_ashrrev_i32_e32 v5, 31, v3
	v_or_b32_e32 v4, 0x80000000, v4
	v_or_b32_e32 v5, 0x80000000, v5
	v_xor_b32_e32 v2, v2, v4
	v_xor_b32_e32 v3, v3, v5
	v_or_b32_e32 v6, 6, v8
	v_cmp_le_i32_e64 s[98:99], v6, v0
	v_or_b32_e32 v7, 7, v8
	s_nop 0
	v_cndmask_b32_e64 v214, 0, v2, s[98:99]
	v_cmp_le_i32_e64 s[98:99], v7, v0
	s_nop 1
	v_cndmask_b32_e64 v213, 0, v3, s[98:99]
	v_pk_add_f32 v[2:3], v[24:25], 0 op_sel_hi:[1,0]
	v_ashrrev_i32_e32 v4, 31, v2
	v_ashrrev_i32_e32 v5, 31, v3
	v_or_b32_e32 v4, 0x80000000, v4
	v_or_b32_e32 v5, 0x80000000, v5
	v_xor_b32_e32 v2, v2, v4
	v_xor_b32_e32 v3, v3, v5
	v_or_b32_e32 v6, 16, v8
	v_cmp_le_i32_e64 s[98:99], v6, v0
	v_or_b32_e32 v7, 17, v8
	s_nop 0
	v_cndmask_b32_e64 v216, 0, v2, s[98:99]
	v_cmp_le_i32_e64 s[98:99], v7, v0
	s_nop 1
	v_cndmask_b32_e64 v215, 0, v3, s[98:99]
	v_pk_add_f32 v[2:3], v[22:23], 0 op_sel_hi:[1,0]
	v_ashrrev_i32_e32 v4, 31, v2
	v_ashrrev_i32_e32 v5, 31, v3
	v_or_b32_e32 v4, 0x80000000, v4
	v_or_b32_e32 v5, 0x80000000, v5
	v_xor_b32_e32 v2, v2, v4
	v_xor_b32_e32 v3, v3, v5
	v_or_b32_e32 v6, 18, v8
	v_cmp_le_i32_e64 s[98:99], v6, v0
	v_or_b32_e32 v7, 19, v8
	s_nop 0
	v_cndmask_b32_e64 v218, 0, v2, s[98:99]
	v_cmp_le_i32_e64 s[98:99], v7, v0
	s_nop 1
	v_cndmask_b32_e64 v217, 0, v3, s[98:99]
	v_pk_add_f32 v[2:3], v[20:21], 0 op_sel_hi:[1,0]
	v_ashrrev_i32_e32 v4, 31, v2
	v_ashrrev_i32_e32 v5, 31, v3
	v_or_b32_e32 v4, 0x80000000, v4
	v_or_b32_e32 v5, 0x80000000, v5
	v_xor_b32_e32 v2, v2, v4
	v_xor_b32_e32 v3, v3, v5
	v_or_b32_e32 v6, 20, v8
	v_cmp_le_i32_e64 s[98:99], v6, v0
	v_or_b32_e32 v7, 21, v8
	s_nop 0
	v_cndmask_b32_e64 v220, 0, v2, s[98:99]
	v_cmp_le_i32_e64 s[98:99], v7, v0
	s_nop 1
	v_cndmask_b32_e64 v219, 0, v3, s[98:99]
	v_pk_add_f32 v[2:3], v[18:19], 0 op_sel_hi:[1,0]
	v_ashrrev_i32_e32 v4, 31, v2
	v_ashrrev_i32_e32 v5, 31, v3
	v_or_b32_e32 v4, 0x80000000, v4
	v_or_b32_e32 v5, 0x80000000, v5
	v_xor_b32_e32 v2, v2, v4
	v_xor_b32_e32 v3, v3, v5
	v_or_b32_e32 v6, 22, v8
	v_cmp_le_i32_e64 s[98:99], v6, v0
	v_or_b32_e32 v7, 23, v8
	s_nop 0
	v_cndmask_b32_e64 v222, 0, v2, s[98:99]
	v_cmp_le_i32_e64 s[98:99], v7, v0
	s_nop 1
	v_cndmask_b32_e64 v221, 0, v3, s[98:99]
	s_branch .Lkc_done_418
; DI void a1_task(unsigned char* shm, const bf16_t* prm, const bf16_t* prt, unsigned* mask, int b, int qt, const int tid) {
;     ...
;             for (int i = 0; i < 16; ++i) {
;                 const int s = s0 + 16 * (i >> 3) + 8 * h + (i & 7);
;                 const unsigned u = __float_as_uint(idx[i] + 0.0f);
;                 const unsigned k = (u & 0x80000000u) ? ~u : (u | 0x80000000u);
;                 key[jt][i] = (s <= t0 + r) ? k : 0u;
;             }
;             if (hn) {
; #pragma unroll
;                 for (int ks = 0; ks < 4; ++ks) kf[ks] = kn[ks];
;             }
.Lkc_full_418:
	v_pk_add_f32 v[2:3], v[32:33], 0 op_sel_hi:[1,0]
	v_ashrrev_i32_e32 v4, 31, v2
	v_ashrrev_i32_e32 v5, 31, v3
	v_or_b32_e32 v4, 0x80000000, v4
	v_or_b32_e32 v5, 0x80000000, v5
	v_xor_b32_e32 v191, v2, v4
	v_xor_b32_e32 v190, v3, v5
	v_pk_add_f32 v[2:3], v[30:31], 0 op_sel_hi:[1,0]
	v_ashrrev_i32_e32 v4, 31, v2
	v_ashrrev_i32_e32 v5, 31, v3
	v_or_b32_e32 v4, 0x80000000, v4
	v_or_b32_e32 v5, 0x80000000, v5
	v_xor_b32_e32 v193, v2, v4
	v_xor_b32_e32 v192, v3, v5
	v_pk_add_f32 v[2:3], v[28:29], 0 op_sel_hi:[1,0]
	v_ashrrev_i32_e32 v4, 31, v2
	v_ashrrev_i32_e32 v5, 31, v3
	v_or_b32_e32 v4, 0x80000000, v4
	v_or_b32_e32 v5, 0x80000000, v5
	v_xor_b32_e32 v212, v2, v4
	v_xor_b32_e32 v211, v3, v5
	v_pk_add_f32 v[2:3], v[26:27], 0 op_sel_hi:[1,0]
	v_ashrrev_i32_e32 v4, 31, v2
	v_ashrrev_i32_e32 v5, 31, v3
	v_or_b32_e32 v4, 0x80000000, v4
	v_or_b32_e32 v5, 0x80000000, v5
	v_xor_b32_e32 v214, v2, v4
	v_xor_b32_e32 v213, v3, v5
	v_pk_add_f32 v[2:3], v[24:25], 0 op_sel_hi:[1,0]
	v_ashrrev_i32_e32 v4, 31, v2
	v_ashrrev_i32_e32 v5, 31, v3
	v_or_b32_e32 v4, 0x80000000, v4
	v_or_b32_e32 v5, 0x80000000, v5
	v_xor_b32_e32 v216, v2, v4
	v_xor_b32_e32 v215, v3, v5
	v_pk_add_f32 v[2:3], v[22:23], 0 op_sel_hi:[1,0]
	v_ashrrev_i32_e32 v4, 31, v2
	v_ashrrev_i32_e32 v5, 31, v3
	v_or_b32_e32 v4, 0x80000000, v4
	v_or_b32_e32 v5, 0x80000000, v5
	v_xor_b32_e32 v218, v2, v4
	v_xor_b32_e32 v217, v3, v5
	v_pk_add_f32 v[2:3], v[20:21], 0 op_sel_hi:[1,0]
	v_ashrrev_i32_e32 v4, 31, v2
	v_ashrrev_i32_e32 v5, 31, v3
	v_or_b32_e32 v4, 0x80000000, v4
	v_or_b32_e32 v5, 0x80000000, v5
	v_xor_b32_e32 v220, v2, v4
	v_xor_b32_e32 v219, v3, v5
	v_pk_add_f32 v[2:3], v[18:19], 0 op_sel_hi:[1,0]
	v_ashrrev_i32_e32 v4, 31, v2
	v_ashrrev_i32_e32 v5, 31, v3
	v_or_b32_e32 v4, 0x80000000, v4
	v_or_b32_e32 v5, 0x80000000, v5
	v_xor_b32_e32 v222, v2, v4
	v_xor_b32_e32 v221, v3, v5
.Lkc_done_418:
	v_mov_b64_e32 v[72:73], v[68:69]
	v_mov_b64_e32 v[80:81], v[76:77]
	v_mov_b64_e32 v[88:89], v[84:85]
	v_mov_b64_e32 v[96:97], v[92:93]
	s_andn2_b64 vcc, exec, s[40:41]
	v_mov_b64_e32 v[70:71], v[66:67]
	v_mov_b64_e32 v[78:79], v[74:75]
	v_mov_b64_e32 v[86:87], v[82:83]
	v_mov_b64_e32 v[94:95], v[90:91]
	s_cbranch_vccnz .LBB0_421
	s_waitcnt vmcnt(3)
	v_mov_b64_e32 v[72:73], v[36:37]
	s_waitcnt vmcnt(2)
	v_mov_b64_e32 v[80:81], v[40:41]
	s_waitcnt vmcnt(1)
	v_mov_b64_e32 v[88:89], v[44:45]
	s_waitcnt vmcnt(0)
	v_mov_b64_e32 v[96:97], v[48:49]
	v_mov_b64_e32 v[70:71], v[34:35]
	v_mov_b64_e32 v[78:79], v[38:39]
	v_mov_b64_e32 v[86:87], v[42:43]
	v_mov_b64_e32 v[94:95], v[46:47]

; #define MFMA32(a, b, c) __builtin_amdgcn_mfma_f32_32x32x16_bf16((a), (b), (c), 0, 0, 0)
; DI void a1_task(unsigned char* shm, const bf16_t* prm, const bf16_t* prt, unsigned* mask, int b, int qt, const int tid) {
;     ...
;             for (int hh = 0; hh < 8; ++hh) {
;                 bf16x8 qa[4];
; #pragma unroll
;                 for (int ks = 0; ks < 4; ++ks) qa[ks] = *(const bf16x8*)(qb0 + hh * 128 + 32 * ks);
;                 const float wv = wqs[hh * 32 + r];
;                 asm volatile("s_waitcnt lgkmcnt(0)" ::: "memory");
;                 f32x16 acc;
; #pragma unroll
;                 for (int i = 0; i < 16; ++i) acc[i] = 0.f;
; #pragma unroll
;                 for (int ks = 0; ks < 4; ++ks) acc = MFMA32(kf[ks], qa[ks], acc);
; #pragma unroll
;                 for (int i = 0; i < 16; ++i) idx[i] = fmaf(wv, fmaxf(acc[i], 0.f), idx[i]);
;             }
; #pragma unroll
;             for (int i = 0; i < 16; ++i) {
;                 const int s = s0 + 16 * (i >> 3) + 8 * h + (i & 7);
;                 const unsigned u = __float_as_uint(idx[i] + 0.0f);
;                 const unsigned k = (u & 0x80000000u) ? ~u : (u | 0x80000000u);
;                 key[jt][i] = (s <= t0 + r) ? k : 0u;
;             }
.LBB0_428:
	v_add_u32_e32 v91, s1, v118
	ds_read_b128 v[2:5], v91
	ds_read_b128 v[66:69], v91 offset:32
	ds_read_b128 v[74:77], v91 offset:64
	ds_read_b128 v[82:85], v91 offset:96
	v_add_u32_e32 v92, s1, v135
	s_waitcnt lgkmcnt(3)
	v_mfma_f32_32x32x16_bf16 v[2:17], v[70:73], v[2:5], 0
	ds_read_b32 v90, v92
	s_waitcnt lgkmcnt(0)
	s_addk_i32 s1, 0x100
	s_cmpk_lg_i32 s1, 0x400
	s_waitcnt lgkmcnt(3)
	v_mfma_f32_32x32x16_bf16 v[2:17], v[78:81], v[66:69], v[2:17]
	s_waitcnt lgkmcnt(2)
	v_mfma_f32_32x32x16_bf16 v[2:17], v[86:89], v[74:77], v[2:17]
	s_waitcnt lgkmcnt(1)
	v_mfma_f32_32x32x16_bf16 v[2:17], v[94:97], v[82:85], v[2:17]
	s_nop 11
	v_max_f32_e32 v2, 0, v2
	v_max_f32_e32 v3, 0, v3
	s_waitcnt lgkmcnt(0)
	v_pk_fma_f32 v[64:65], v[90:91], v[2:3], v[64:65] op_sel_hi:[0,1,1]
	v_max_f32_e32 v2, 0, v4
	v_max_f32_e32 v3, 0, v5
	v_pk_fma_f32 v[62:63], v[90:91], v[2:3], v[62:63] op_sel_hi:[0,1,1]
	v_max_f32_e32 v2, 0, v6
	v_max_f32_e32 v3, 0, v7
	v_pk_fma_f32 v[60:61], v[90:91], v[2:3], v[60:61] op_sel_hi:[0,1,1]
	v_max_f32_e32 v2, 0, v8
	v_max_f32_e32 v3, 0, v9
	v_pk_fma_f32 v[58:59], v[90:91], v[2:3], v[58:59] op_sel_hi:[0,1,1]
	v_max_f32_e32 v2, 0, v10
	v_max_f32_e32 v3, 0, v11
	v_pk_fma_f32 v[56:57], v[90:91], v[2:3], v[56:57] op_sel_hi:[0,1,1]
	v_max_f32_e32 v2, 0, v12
	v_max_f32_e32 v3, 0, v13
	v_pk_fma_f32 v[54:55], v[90:91], v[2:3], v[54:55] op_sel_hi:[0,1,1]
	v_max_f32_e32 v2, 0, v14
	v_max_f32_e32 v3, 0, v15
	v_pk_fma_f32 v[52:53], v[90:91], v[2:3], v[52:53] op_sel_hi:[0,1,1]
	v_max_f32_e32 v2, 0, v16
	v_max_f32_e32 v3, 0, v17
	v_pk_fma_f32 v[50:51], v[90:91], v[2:3], v[50:51] op_sel_hi:[0,1,1]
	ds_read_b128 v[2:5], v91 offset:128
	ds_read_b128 v[66:69], v91 offset:160
	ds_read_b128 v[74:77], v91 offset:192
	ds_read_b128 v[82:85], v91 offset:224
	ds_read_b32 v90, v92 offset:128
	s_waitcnt lgkmcnt(4)
	v_mfma_f32_32x32x16_bf16 v[2:17], v[70:73], v[2:5], 0
	s_waitcnt lgkmcnt(0)
	s_waitcnt lgkmcnt(3)
	v_mfma_f32_32x32x16_bf16 v[2:17], v[78:81], v[66:69], v[2:17]
	s_waitcnt lgkmcnt(2)
	v_mfma_f32_32x32x16_bf16 v[2:17], v[86:89], v[74:77], v[2:17]
	s_waitcnt lgkmcnt(1)
	v_mfma_f32_32x32x16_bf16 v[2:17], v[94:97], v[82:85], v[2:17]
	s_nop 11
	v_max_f32_e32 v2, 0, v2
	v_max_f32_e32 v3, 0, v3
	s_waitcnt lgkmcnt(0)
	v_pk_fma_f32 v[64:65], v[90:91], v[2:3], v[64:65] op_sel_hi:[0,1,1]
	v_max_f32_e32 v2, 0, v4
	v_max_f32_e32 v3, 0, v5
	v_pk_fma_f32 v[62:63], v[90:91], v[2:3], v[62:63] op_sel_hi:[0,1,1]
	v_max_f32_e32 v2, 0, v6
	v_max_f32_e32 v3, 0, v7
	v_pk_fma_f32 v[60:61], v[90:91], v[2:3], v[60:61] op_sel_hi:[0,1,1]
	v_max_f32_e32 v2, 0, v8
	v_max_f32_e32 v3, 0, v9
	v_pk_fma_f32 v[58:59], v[90:91], v[2:3], v[58:59] op_sel_hi:[0,1,1]
	v_max_f32_e32 v2, 0, v10
	v_max_f32_e32 v3, 0, v11
	v_pk_fma_f32 v[56:57], v[90:91], v[2:3], v[56:57] op_sel_hi:[0,1,1]
	v_max_f32_e32 v2, 0, v12
	v_max_f32_e32 v3, 0, v13
	v_pk_fma_f32 v[54:55], v[90:91], v[2:3], v[54:55] op_sel_hi:[0,1,1]
	v_max_f32_e32 v2, 0, v14
	v_max_f32_e32 v3, 0, v15
	v_pk_fma_f32 v[52:53], v[90:91], v[2:3], v[52:53] op_sel_hi:[0,1,1]
	v_max_f32_e32 v2, 0, v16
	v_max_f32_e32 v3, 0, v17
	v_pk_fma_f32 v[50:51], v[90:91], v[2:3], v[50:51] op_sel_hi:[0,1,1]
	s_cbranch_scc1 .LBB0_428
	v_or_b32_e32 v8, s0, v98
	s_lshr_b32 s98, s0, 5
	s_cmp_lt_u32 s98, s2
	s_cbranch_scc1 .Lkc_full_428
	v_pk_add_f32 v[2:3], v[64:65], 0 op_sel_hi:[1,0]
	v_ashrrev_i32_e32 v4, 31, v2
	v_ashrrev_i32_e32 v5, 31, v3
	v_or_b32_e32 v4, 0x80000000, v4
	v_or_b32_e32 v5, 0x80000000, v5
	v_xor_b32_e32 v2, v2, v4
	v_xor_b32_e32 v3, v3, v5
	v_mov_b32_e32 v6, v8
	v_cmp_le_i32_e64 s[98:99], v6, v0
	v_or_b32_e32 v7, 1, v8
	s_nop 0
	v_cndmask_b32_e64 v83, 0, v2, s[98:99]
	v_cmp_le_i32_e64 s[98:99], v7, v0
	s_nop 1
	v_cndmask_b32_e64 v82, 0, v3, s[98:99]
	v_pk_add_f32 v[2:3], v[62:63], 0 op_sel_hi:[1,0]
	v_ashrrev_i32_e32 v4, 31, v2
	v_ashrrev_i32_e32 v5, 31, v3
	v_or_b32_e32 v4, 0x80000000, v4
	v_or_b32_e32 v5, 0x80000000, v5
	v_xor_b32_e32 v2, v2, v4
	v_xor_b32_e32 v3, v3, v5
	v_or_b32_e32 v6, 2, v8
	v_cmp_le_i32_e64 s[98:99], v6, v0
	v_or_b32_e32 v7, 3, v8
	s_nop 0
	v_cndmask_b32_e64 v85, 0, v2, s[98:99]
	v_cmp_le_i32_e64 s[98:99], v7, v0
	s_nop 1
	v_cndmask_b32_e64 v84, 0, v3, s[98:99]
	v_pk_add_f32 v[2:3], v[60:61], 0 op_sel_hi:[1,0]
	v_ashrrev_i32_e32 v4, 31, v2
	v_ashrrev_i32_e32 v5, 31, v3
	v_or_b32_e32 v4, 0x80000000, v4
	v_or_b32_e32 v5, 0x80000000, v5
	v_xor_b32_e32 v2, v2, v4
	v_xor_b32_e32 v3, v3, v5
	v_or_b32_e32 v6, 4, v8
	v_cmp_le_i32_e64 s[98:99], v6, v0
	v_or_b32_e32 v7, 5, v8
	s_nop 0
	v_cndmask_b32_e64 v91, 0, v2, s[98:99]
	v_cmp_le_i32_e64 s[98:99], v7, v0
	s_nop 1
	v_cndmask_b32_e64 v90, 0, v3, s[98:99]
	v_pk_add_f32 v[2:3], v[58:59], 0 op_sel_hi:[1,0]
	v_ashrrev_i32_e32 v4, 31, v2
	v_ashrrev_i32_e32 v5, 31, v3
	v_or_b32_e32 v4, 0x80000000, v4
	v_or_b32_e32 v5, 0x80000000, v5
	v_xor_b32_e32 v2, v2, v4
	v_xor_b32_e32 v3, v3, v5
	v_or_b32_e32 v6, 6, v8
	v_cmp_le_i32_e64 s[98:99], v6, v0
	v_or_b32_e32 v7, 7, v8
	s_nop 0
	v_cndmask_b32_e64 v93, 0, v2, s[98:99]
	v_cmp_le_i32_e64 s[98:99], v7, v0
	s_nop 1
	v_cndmask_b32_e64 v92, 0, v3, s[98:99]
	v_pk_add_f32 v[2:3], v[56:57], 0 op_sel_hi:[1,0]
	v_ashrrev_i32_e32 v4, 31, v2
	v_ashrrev_i32_e32 v5, 31, v3
	v_or_b32_e32 v4, 0x80000000, v4
	v_or_b32_e32 v5, 0x80000000, v5
	v_xor_b32_e32 v2, v2, v4
	v_xor_b32_e32 v3, v3, v5
	v_or_b32_e32 v6, 16, v8
	v_cmp_le_i32_e64 s[98:99], v6, v0
	v_or_b32_e32 v7, 17, v8
	s_nop 0
	v_cndmask_b32_e64 v224, 0, v2, s[98:99]
	v_cmp_le_i32_e64 s[98:99], v7, v0
	s_nop 1
	v_cndmask_b32_e64 v223, 0, v3, s[98:99]
	v_pk_add_f32 v[2:3], v[54:55], 0 op_sel_hi:[1,0]
	v_ashrrev_i32_e32 v4, 31, v2
	v_ashrrev_i32_e32 v5, 31, v3
	v_or_b32_e32 v4, 0x80000000, v4
	v_or_b32_e32 v5, 0x80000000, v5
	v_xor_b32_e32 v2, v2, v4
	v_xor_b32_e32 v3, v3, v5
	v_or_b32_e32 v6, 18, v8
	v_cmp_le_i32_e64 s[98:99], v6, v0
	v_or_b32_e32 v7, 19, v8
	s_nop 0
	v_cndmask_b32_e64 v226, 0, v2, s[98:99]
	v_cmp_le_i32_e64 s[98:99], v7, v0
	s_nop 1
	v_cndmask_b32_e64 v225, 0, v3, s[98:99]
	v_pk_add_f32 v[2:3], v[52:53], 0 op_sel_hi:[1,0]
	v_ashrrev_i32_e32 v4, 31, v2
	v_ashrrev_i32_e32 v5, 31, v3
	v_or_b32_e32 v4, 0x80000000, v4
	v_or_b32_e32 v5, 0x80000000, v5
	v_xor_b32_e32 v2, v2, v4
	v_xor_b32_e32 v3, v3, v5
	v_or_b32_e32 v6, 20, v8
	v_cmp_le_i32_e64 s[98:99], v6, v0
	v_or_b32_e32 v7, 21, v8
	s_nop 0
	v_cndmask_b32_e64 v228, 0, v2, s[98:99]
	v_cmp_le_i32_e64 s[98:99], v7, v0
	s_nop 1
	v_cndmask_b32_e64 v227, 0, v3, s[98:99]
	v_pk_add_f32 v[2:3], v[50:51], 0 op_sel_hi:[1,0]
	v_ashrrev_i32_e32 v4, 31, v2
	v_ashrrev_i32_e32 v5, 31, v3
	v_or_b32_e32 v4, 0x80000000, v4
	v_or_b32_e32 v5, 0x80000000, v5
	v_xor_b32_e32 v2, v2, v4
	v_xor_b32_e32 v3, v3, v5
	v_or_b32_e32 v6, 22, v8
	v_cmp_le_i32_e64 s[98:99], v6, v0
	v_or_b32_e32 v7, 23, v8
	s_nop 0
	v_cndmask_b32_e64 v230, 0, v2, s[98:99]
	v_cmp_le_i32_e64 s[98:99], v7, v0
	s_nop 1
	v_cndmask_b32_e64 v229, 0, v3, s[98:99]
	s_branch .Lkc_done_428
; DI void a1_task(unsigned char* shm, const bf16_t* prm, const bf16_t* prt, unsigned* mask, int b, int qt, const int tid) {
;     ...
;             for (int i = 0; i < 16; ++i) {
;                 const int s = s0 + 16 * (i >> 3) + 8 * h + (i & 7);
;                 const unsigned u = __float_as_uint(idx[i] + 0.0f);
;                 const unsigned k = (u & 0x80000000u) ? ~u : (u | 0x80000000u);
;                 key[jt][i] = (s <= t0 + r) ? k : 0u;
;             }
;             if (hn) {
; #pragma unroll
;                 for (int ks = 0; ks < 4; ++ks) kf[ks] = kn[ks];
.Lkc_full_428:
	v_pk_add_f32 v[2:3], v[64:65], 0 op_sel_hi:[1,0]
	v_ashrrev_i32_e32 v4, 31, v2
	v_ashrrev_i32_e32 v5, 31, v3
	v_or_b32_e32 v4, 0x80000000, v4
	v_or_b32_e32 v5, 0x80000000, v5
	v_xor_b32_e32 v83, v2, v4
	v_xor_b32_e32 v82, v3, v5
	v_pk_add_f32 v[2:3], v[62:63], 0 op_sel_hi:[1,0]
	v_ashrrev_i32_e32 v4, 31, v2
	v_ashrrev_i32_e32 v5, 31, v3
	v_or_b32_e32 v4, 0x80000000, v4
	v_or_b32_e32 v5, 0x80000000, v5
	v_xor_b32_e32 v85, v2, v4
	v_xor_b32_e32 v84, v3, v5
	v_pk_add_f32 v[2:3], v[60:61], 0 op_sel_hi:[1,0]
	v_ashrrev_i32_e32 v4, 31, v2
	v_ashrrev_i32_e32 v5, 31, v3
	v_or_b32_e32 v4, 0x80000000, v4
	v_or_b32_e32 v5, 0x80000000, v5
	v_xor_b32_e32 v91, v2, v4
	v_xor_b32_e32 v90, v3, v5
	v_pk_add_f32 v[2:3], v[58:59], 0 op_sel_hi:[1,0]
	v_ashrrev_i32_e32 v4, 31, v2
	v_ashrrev_i32_e32 v5, 31, v3
	v_or_b32_e32 v4, 0x80000000, v4
	v_or_b32_e32 v5, 0x80000000, v5
	v_xor_b32_e32 v93, v2, v4
	v_xor_b32_e32 v92, v3, v5
	v_pk_add_f32 v[2:3], v[56:57], 0 op_sel_hi:[1,0]
	v_ashrrev_i32_e32 v4, 31, v2
	v_ashrrev_i32_e32 v5, 31, v3
	v_or_b32_e32 v4, 0x80000000, v4
	v_or_b32_e32 v5, 0x80000000, v5
	v_xor_b32_e32 v224, v2, v4
	v_xor_b32_e32 v223, v3, v5
	v_pk_add_f32 v[2:3], v[54:55], 0 op_sel_hi:[1,0]
	v_ashrrev_i32_e32 v4, 31, v2
	v_ashrrev_i32_e32 v5, 31, v3
	v_or_b32_e32 v4, 0x80000000, v4
	v_or_b32_e32 v5, 0x80000000, v5
	v_xor_b32_e32 v226, v2, v4
	v_xor_b32_e32 v225, v3, v5
	v_pk_add_f32 v[2:3], v[52:53], 0 op_sel_hi:[1,0]
	v_ashrrev_i32_e32 v4, 31, v2
	v_ashrrev_i32_e32 v5, 31, v3
	v_or_b32_e32 v4, 0x80000000, v4
	v_or_b32_e32 v5, 0x80000000, v5
	v_xor_b32_e32 v228, v2, v4
	v_xor_b32_e32 v227, v3, v5
	v_pk_add_f32 v[2:3], v[50:51], 0 op_sel_hi:[1,0]
	v_ashrrev_i32_e32 v4, 31, v2
	v_ashrrev_i32_e32 v5, 31, v3
	v_or_b32_e32 v4, 0x80000000, v4
	v_or_b32_e32 v5, 0x80000000, v5
	v_xor_b32_e32 v230, v2, v4
	v_xor_b32_e32 v229, v3, v5
.Lkc_done_428:
	v_mov_b64_e32 v[50:51], v[70:71]
	v_mov_b64_e32 v[54:55], v[78:79]
	v_mov_b64_e32 v[58:59], v[86:87]
	v_mov_b64_e32 v[62:63], v[94:95]
	s_andn2_b64 vcc, exec, s[40:41]
	v_mov_b64_e32 v[52:53], v[72:73]
	v_mov_b64_e32 v[56:57], v[80:81]
	v_mov_b64_e32 v[60:61], v[88:89]
	v_mov_b64_e32 v[64:65], v[96:97]
	s_cbranch_vccnz .LBB0_431
	s_waitcnt vmcnt(3)
	v_mov_b64_e32 v[52:53], v[20:21]
	s_waitcnt vmcnt(2)
	v_mov_b64_e32 v[56:57], v[24:25]
	s_waitcnt vmcnt(1)
	v_mov_b64_e32 v[60:61], v[28:29]
	s_waitcnt vmcnt(0)
	v_mov_b64_e32 v[64:65], v[32:33]
	v_mov_b64_e32 v[50:51], v[18:19]
	v_mov_b64_e32 v[54:55], v[22:23]
	v_mov_b64_e32 v[58:59], v[26:27]
	v_mov_b64_e32 v[62:63], v[30:31]
.LBB0_431:
	s_mov_b64 s[96:97], 0x2c0000
	v_readlane_b32 s6, v255, 40
	v_readlane_b32 s88, v254, 41
	v_readlane_b32 s94, v254, 47
	v_readlane_b32 s95, v254, 48
	v_readlane_b32 s80, v254, 51
	v_readlane_b32 s86, v254, 39
	v_readlane_b32 s56, v254, 49
	v_readlane_b32 s81, v254, 52
	v_readlane_b32 s84, v254, 59
	v_readlane_b32 s94, v254, 61
	v_readlane_b32 s60, v254, 63
	v_readlane_b32 s76, v255, 15
	v_readlane_b32 s78, v255, 17
	v_readlane_b32 s58, v255, 33
	s_mov_b64 s[0:1], 0
	v_readlane_b32 s87, v254, 40
	v_readlane_b32 s89, v254, 42
	v_readlane_b32 s90, v254, 43
	v_readlane_b32 s91, v254, 44
	v_readlane_b32 s92, v254, 45
	v_readlane_b32 s93, v254, 46
	v_readlane_b32 s57, v254, 50
	v_readlane_b32 s85, v254, 60
	v_readlane_b32 s95, v254, 62
	v_readlane_b32 s61, v255, 0
	v_readlane_b32 s62, v255, 1
	v_readlane_b32 s63, v255, 2
	v_readlane_b32 s64, v255, 3
	v_readlane_b32 s65, v255, 4
	v_readlane_b32 s66, v255, 5
	v_readlane_b32 s67, v255, 6
	v_readlane_b32 s68, v255, 7
	v_readlane_b32 s69, v255, 8
	v_readlane_b32 s70, v255, 9
	v_readlane_b32 s71, v255, 10
	v_readlane_b32 s72, v255, 11
	v_readlane_b32 s73, v255, 12
	v_readlane_b32 s74, v255, 13
	v_readlane_b32 s75, v255, 14
	v_readlane_b32 s77, v255, 16
	v_readlane_b32 s79, v255, 18
	v_readlane_b32 s81, v254, 1
	s_mov_b64 s[82:83], 0x58000
	v_readlane_b32 s59, v255, 34
	v_readlane_b32 s4, v255, 56
	v_readlane_b32 s7, v255, 41
	v_readlane_b32 s5, v255, 57

; #define MFMA32(a, b, c) __builtin_amdgcn_mfma_f32_32x32x16_bf16((a), (b), (c), 0, 0, 0)
; DI void a1_task(unsigned char* shm, const bf16_t* prm, const bf16_t* prt, unsigned* mask, int b, int qt, const int tid) {
;     ...
;             for (int hh = 0; hh < 8; ++hh) {
;                 bf16x8 qa[4];
; #pragma unroll
;                 for (int ks = 0; ks < 4; ++ks) qa[ks] = *(const bf16x8*)(qb0 + hh * 128 + 32 * ks);
;                 const float wv = wqs[hh * 32 + r];
;                 asm volatile("s_waitcnt lgkmcnt(0)" ::: "memory");
;                 f32x16 acc;
; #pragma unroll
;                 for (int i = 0; i < 16; ++i) acc[i] = 0.f;
; #pragma unroll
;                 for (int ks = 0; ks < 4; ++ks) acc = MFMA32(kf[ks], qa[ks], acc);
; #pragma unroll
;                 for (int i = 0; i < 16; ++i) idx[i] = fmaf(wv, fmaxf(acc[i], 0.f), idx[i]);
;             }
; #pragma unroll
;             for (int i = 0; i < 16; ++i) {
;                 const int s = s0 + 16 * (i >> 3) + 8 * h + (i & 7);
;                 const unsigned u = __float_as_uint(idx[i] + 0.0f);
;                 const unsigned k = (u & 0x80000000u) ? ~u : (u | 0x80000000u);
;                 key[jt][i] = (s <= t0 + r) ? k : 0u;
;             }
.LBB0_438:
	v_add_u32_e32 v199, s1, v118
	ds_read_b128 v[2:5], v199
	ds_read_b128 v[86:89], v199 offset:32
	ds_read_b128 v[94:97], v199 offset:64
	ds_read_b128 v[244:247], v199 offset:96
	v_add_u32_e32 v200, s1, v135
	s_waitcnt lgkmcnt(3)
	v_mfma_f32_32x32x16_bf16 v[2:17], v[50:53], v[2:5], 0
	ds_read_b32 v198, v200
	s_waitcnt lgkmcnt(0)
	s_addk_i32 s1, 0x100
	s_cmpk_lg_i32 s1, 0x400
	s_waitcnt lgkmcnt(3)
	v_mfma_f32_32x32x16_bf16 v[2:17], v[54:57], v[86:89], v[2:17]
	s_waitcnt lgkmcnt(2)
	v_mfma_f32_32x32x16_bf16 v[2:17], v[58:61], v[94:97], v[2:17]
	s_waitcnt lgkmcnt(1)
	v_mfma_f32_32x32x16_bf16 v[2:17], v[62:65], v[244:247], v[2:17]
	s_nop 11
	v_max_f32_e32 v2, 0, v2
	v_max_f32_e32 v3, 0, v3
	s_waitcnt lgkmcnt(0)
	v_pk_fma_f32 v[80:81], v[198:199], v[2:3], v[80:81] op_sel_hi:[0,1,1]
	v_max_f32_e32 v2, 0, v4
	v_max_f32_e32 v3, 0, v5
	v_pk_fma_f32 v[78:79], v[198:199], v[2:3], v[78:79] op_sel_hi:[0,1,1]
	v_max_f32_e32 v2, 0, v6
	v_max_f32_e32 v3, 0, v7
	v_pk_fma_f32 v[76:77], v[198:199], v[2:3], v[76:77] op_sel_hi:[0,1,1]
	v_max_f32_e32 v2, 0, v8
	v_max_f32_e32 v3, 0, v9
	v_pk_fma_f32 v[74:75], v[198:199], v[2:3], v[74:75] op_sel_hi:[0,1,1]
	v_max_f32_e32 v2, 0, v10
	v_max_f32_e32 v3, 0, v11
	v_pk_fma_f32 v[72:73], v[198:199], v[2:3], v[72:73] op_sel_hi:[0,1,1]
	v_max_f32_e32 v2, 0, v12
	v_max_f32_e32 v3, 0, v13
	v_pk_fma_f32 v[70:71], v[198:199], v[2:3], v[70:71] op_sel_hi:[0,1,1]
	v_max_f32_e32 v2, 0, v14
	v_max_f32_e32 v3, 0, v15
	v_pk_fma_f32 v[68:69], v[198:199], v[2:3], v[68:69] op_sel_hi:[0,1,1]
	v_max_f32_e32 v2, 0, v16
	v_max_f32_e32 v3, 0, v17
	v_pk_fma_f32 v[66:67], v[198:199], v[2:3], v[66:67] op_sel_hi:[0,1,1]
	ds_read_b128 v[2:5], v199 offset:128
	ds_read_b128 v[86:89], v199 offset:160
	ds_read_b128 v[94:97], v199 offset:192
	ds_read_b128 v[244:247], v199 offset:224
	ds_read_b32 v198, v200 offset:128
	s_waitcnt lgkmcnt(4)
	v_mfma_f32_32x32x16_bf16 v[2:17], v[50:53], v[2:5], 0
	s_waitcnt lgkmcnt(0)
	s_waitcnt lgkmcnt(3)
	v_mfma_f32_32x32x16_bf16 v[2:17], v[54:57], v[86:89], v[2:17]
	s_waitcnt lgkmcnt(2)
	v_mfma_f32_32x32x16_bf16 v[2:17], v[58:61], v[94:97], v[2:17]
	s_waitcnt lgkmcnt(1)
	v_mfma_f32_32x32x16_bf16 v[2:17], v[62:65], v[244:247], v[2:17]
	s_nop 11
	v_max_f32_e32 v2, 0, v2
	v_max_f32_e32 v3, 0, v3
	s_waitcnt lgkmcnt(0)
	v_pk_fma_f32 v[80:81], v[198:199], v[2:3], v[80:81] op_sel_hi:[0,1,1]
	v_max_f32_e32 v2, 0, v4
	v_max_f32_e32 v3, 0, v5
	v_pk_fma_f32 v[78:79], v[198:199], v[2:3], v[78:79] op_sel_hi:[0,1,1]
	v_max_f32_e32 v2, 0, v6
	v_max_f32_e32 v3, 0, v7
	v_pk_fma_f32 v[76:77], v[198:199], v[2:3], v[76:77] op_sel_hi:[0,1,1]
	v_max_f32_e32 v2, 0, v8
	v_max_f32_e32 v3, 0, v9
	v_pk_fma_f32 v[74:75], v[198:199], v[2:3], v[74:75] op_sel_hi:[0,1,1]
	v_max_f32_e32 v2, 0, v10
	v_max_f32_e32 v3, 0, v11
	v_pk_fma_f32 v[72:73], v[198:199], v[2:3], v[72:73] op_sel_hi:[0,1,1]
	v_max_f32_e32 v2, 0, v12
	v_max_f32_e32 v3, 0, v13
	v_pk_fma_f32 v[70:71], v[198:199], v[2:3], v[70:71] op_sel_hi:[0,1,1]
	v_max_f32_e32 v2, 0, v14
	v_max_f32_e32 v3, 0, v15
	v_pk_fma_f32 v[68:69], v[198:199], v[2:3], v[68:69] op_sel_hi:[0,1,1]
	v_max_f32_e32 v2, 0, v16
	v_max_f32_e32 v3, 0, v17
	v_pk_fma_f32 v[66:67], v[198:199], v[2:3], v[66:67] op_sel_hi:[0,1,1]
	s_cbranch_scc1 .LBB0_438
	v_or_b32_e32 v8, s0, v98
	s_lshr_b32 s98, s0, 5
	s_cmp_lt_u32 s98, s2
	s_cbranch_scc1 .Lkc_full_438
	v_pk_add_f32 v[2:3], v[80:81], 0 op_sel_hi:[1,0]
	v_ashrrev_i32_e32 v4, 31, v2
	v_ashrrev_i32_e32 v5, 31, v3
	v_or_b32_e32 v4, 0x80000000, v4
	v_or_b32_e32 v5, 0x80000000, v5
	v_xor_b32_e32 v2, v2, v4
	v_xor_b32_e32 v3, v3, v5
	v_mov_b32_e32 v6, v8
	v_cmp_le_i32_e64 s[98:99], v6, v0
	v_or_b32_e32 v7, 1, v8
	s_nop 0
	v_cndmask_b32_e64 v87, 0, v2, s[98:99]
	v_cmp_le_i32_e64 s[98:99], v7, v0
	s_nop 1
	v_cndmask_b32_e64 v86, 0, v3, s[98:99]
	v_pk_add_f32 v[2:3], v[78:79], 0 op_sel_hi:[1,0]
	v_ashrrev_i32_e32 v4, 31, v2
	v_ashrrev_i32_e32 v5, 31, v3
	v_or_b32_e32 v4, 0x80000000, v4
	v_or_b32_e32 v5, 0x80000000, v5
	v_xor_b32_e32 v2, v2, v4
	v_xor_b32_e32 v3, v3, v5
	v_or_b32_e32 v6, 2, v8
	v_cmp_le_i32_e64 s[98:99], v6, v0
	v_or_b32_e32 v7, 3, v8
	s_nop 0
	v_cndmask_b32_e64 v89, 0, v2, s[98:99]
	v_cmp_le_i32_e64 s[98:99], v7, v0
	s_nop 1
	v_cndmask_b32_e64 v88, 0, v3, s[98:99]
	v_pk_add_f32 v[2:3], v[76:77], 0 op_sel_hi:[1,0]
	v_ashrrev_i32_e32 v4, 31, v2
	v_ashrrev_i32_e32 v5, 31, v3
	v_or_b32_e32 v4, 0x80000000, v4
	v_or_b32_e32 v5, 0x80000000, v5
	v_xor_b32_e32 v2, v2, v4
	v_xor_b32_e32 v3, v3, v5
	v_or_b32_e32 v6, 4, v8
	v_cmp_le_i32_e64 s[98:99], v6, v0
	v_or_b32_e32 v7, 5, v8
	s_nop 0
	v_cndmask_b32_e64 v95, 0, v2, s[98:99]
	v_cmp_le_i32_e64 s[98:99], v7, v0
	s_nop 1
	v_cndmask_b32_e64 v94, 0, v3, s[98:99]
	v_pk_add_f32 v[2:3], v[74:75], 0 op_sel_hi:[1,0]
	v_ashrrev_i32_e32 v4, 31, v2
	v_ashrrev_i32_e32 v5, 31, v3
	v_or_b32_e32 v4, 0x80000000, v4
	v_or_b32_e32 v5, 0x80000000, v5
	v_xor_b32_e32 v2, v2, v4
	v_xor_b32_e32 v3, v3, v5
	v_or_b32_e32 v6, 6, v8
	v_cmp_le_i32_e64 s[98:99], v6, v0
	v_or_b32_e32 v7, 7, v8
	s_nop 0
	v_cndmask_b32_e64 v97, 0, v2, s[98:99]
	v_cmp_le_i32_e64 s[98:99], v7, v0
	s_nop 1
	v_cndmask_b32_e64 v96, 0, v3, s[98:99]
	v_pk_add_f32 v[2:3], v[72:73], 0 op_sel_hi:[1,0]
	v_ashrrev_i32_e32 v4, 31, v2
	v_ashrrev_i32_e32 v5, 31, v3
	v_or_b32_e32 v4, 0x80000000, v4
	v_or_b32_e32 v5, 0x80000000, v5
	v_xor_b32_e32 v2, v2, v4
	v_xor_b32_e32 v3, v3, v5
	v_or_b32_e32 v6, 16, v8
	v_cmp_le_i32_e64 s[98:99], v6, v0
	v_or_b32_e32 v7, 17, v8
	s_nop 0
	v_cndmask_b32_e64 v244, 0, v2, s[98:99]
	v_cmp_le_i32_e64 s[98:99], v7, v0
	s_nop 1
	v_cndmask_b32_e64 v231, 0, v3, s[98:99]
	v_pk_add_f32 v[2:3], v[70:71], 0 op_sel_hi:[1,0]
	v_ashrrev_i32_e32 v4, 31, v2
	v_ashrrev_i32_e32 v5, 31, v3
	v_or_b32_e32 v4, 0x80000000, v4
	v_or_b32_e32 v5, 0x80000000, v5
	v_xor_b32_e32 v2, v2, v4
	v_xor_b32_e32 v3, v3, v5
	v_or_b32_e32 v6, 18, v8
	v_cmp_le_i32_e64 s[98:99], v6, v0
	v_or_b32_e32 v7, 19, v8
	s_nop 0
	v_cndmask_b32_e64 v246, 0, v2, s[98:99]
	v_cmp_le_i32_e64 s[98:99], v7, v0
	s_nop 1
	v_cndmask_b32_e64 v245, 0, v3, s[98:99]
	v_pk_add_f32 v[2:3], v[68:69], 0 op_sel_hi:[1,0]
	v_ashrrev_i32_e32 v4, 31, v2
	v_ashrrev_i32_e32 v5, 31, v3
	v_or_b32_e32 v4, 0x80000000, v4
	v_or_b32_e32 v5, 0x80000000, v5
	v_xor_b32_e32 v2, v2, v4
	v_xor_b32_e32 v3, v3, v5
	v_or_b32_e32 v6, 20, v8
	v_cmp_le_i32_e64 s[98:99], v6, v0
	v_or_b32_e32 v7, 21, v8
	s_nop 0
	v_cndmask_b32_e64 v248, 0, v2, s[98:99]
	v_cmp_le_i32_e64 s[98:99], v7, v0
	s_nop 1
	v_cndmask_b32_e64 v247, 0, v3, s[98:99]
	v_pk_add_f32 v[2:3], v[66:67], 0 op_sel_hi:[1,0]
	v_ashrrev_i32_e32 v4, 31, v2
	v_ashrrev_i32_e32 v5, 31, v3
	v_or_b32_e32 v4, 0x80000000, v4
	v_or_b32_e32 v5, 0x80000000, v5
	v_xor_b32_e32 v2, v2, v4
	v_xor_b32_e32 v3, v3, v5
	v_or_b32_e32 v6, 22, v8
	v_cmp_le_i32_e64 s[98:99], v6, v0
	v_or_b32_e32 v7, 23, v8
	s_nop 0
	v_cndmask_b32_e64 v250, 0, v2, s[98:99]
	v_cmp_le_i32_e64 s[98:99], v7, v0
	s_nop 1
	v_cndmask_b32_e64 v249, 0, v3, s[98:99]
	s_branch .Lkc_done_438
; DI void a1_task(unsigned char* shm, const bf16_t* prm, const bf16_t* prt, unsigned* mask, int b, int qt, const int tid) {
;     ...
;             for (int i = 0; i < 16; ++i) {
;                 const int s = s0 + 16 * (i >> 3) + 8 * h + (i & 7);
;                 const unsigned u = __float_as_uint(idx[i] + 0.0f);
;                 const unsigned k = (u & 0x80000000u) ? ~u : (u | 0x80000000u);
;                 key[jt][i] = (s <= t0 + r) ? k : 0u;
;             }
;             if (hn) {
; #pragma unroll
;                 for (int ks = 0; ks < 4; ++ks) kf[ks] = kn[ks];
.Lkc_full_438:
	v_pk_add_f32 v[2:3], v[80:81], 0 op_sel_hi:[1,0]
	v_ashrrev_i32_e32 v4, 31, v2
	v_ashrrev_i32_e32 v5, 31, v3
	v_or_b32_e32 v4, 0x80000000, v4
	v_or_b32_e32 v5, 0x80000000, v5
	v_xor_b32_e32 v87, v2, v4
	v_xor_b32_e32 v86, v3, v5
	v_pk_add_f32 v[2:3], v[78:79], 0 op_sel_hi:[1,0]
	v_ashrrev_i32_e32 v4, 31, v2
	v_ashrrev_i32_e32 v5, 31, v3
	v_or_b32_e32 v4, 0x80000000, v4
	v_or_b32_e32 v5, 0x80000000, v5
	v_xor_b32_e32 v89, v2, v4
	v_xor_b32_e32 v88, v3, v5
	v_pk_add_f32 v[2:3], v[76:77], 0 op_sel_hi:[1,0]
	v_ashrrev_i32_e32 v4, 31, v2
	v_ashrrev_i32_e32 v5, 31, v3
	v_or_b32_e32 v4, 0x80000000, v4
	v_or_b32_e32 v5, 0x80000000, v5
	v_xor_b32_e32 v95, v2, v4
	v_xor_b32_e32 v94, v3, v5
	v_pk_add_f32 v[2:3], v[74:75], 0 op_sel_hi:[1,0]
	v_ashrrev_i32_e32 v4, 31, v2
	v_ashrrev_i32_e32 v5, 31, v3
	v_or_b32_e32 v4, 0x80000000, v4
	v_or_b32_e32 v5, 0x80000000, v5
	v_xor_b32_e32 v97, v2, v4
	v_xor_b32_e32 v96, v3, v5
	v_pk_add_f32 v[2:3], v[72:73], 0 op_sel_hi:[1,0]
	v_ashrrev_i32_e32 v4, 31, v2
	v_ashrrev_i32_e32 v5, 31, v3
	v_or_b32_e32 v4, 0x80000000, v4
	v_or_b32_e32 v5, 0x80000000, v5
	v_xor_b32_e32 v244, v2, v4
	v_xor_b32_e32 v231, v3, v5
	v_pk_add_f32 v[2:3], v[70:71], 0 op_sel_hi:[1,0]
	v_ashrrev_i32_e32 v4, 31, v2
	v_ashrrev_i32_e32 v5, 31, v3
	v_or_b32_e32 v4, 0x80000000, v4
	v_or_b32_e32 v5, 0x80000000, v5
	v_xor_b32_e32 v246, v2, v4
	v_xor_b32_e32 v245, v3, v5
	v_pk_add_f32 v[2:3], v[68:69], 0 op_sel_hi:[1,0]
	v_ashrrev_i32_e32 v4, 31, v2
	v_ashrrev_i32_e32 v5, 31, v3
	v_or_b32_e32 v4, 0x80000000, v4
	v_or_b32_e32 v5, 0x80000000, v5
	v_xor_b32_e32 v248, v2, v4
	v_xor_b32_e32 v247, v3, v5
	v_pk_add_f32 v[2:3], v[66:67], 0 op_sel_hi:[1,0]
	v_ashrrev_i32_e32 v4, 31, v2
	v_ashrrev_i32_e32 v5, 31, v3
	v_or_b32_e32 v4, 0x80000000, v4
	v_or_b32_e32 v5, 0x80000000, v5
	v_xor_b32_e32 v250, v2, v4
	v_xor_b32_e32 v249, v3, v5
.Lkc_done_438:
	v_mov_b64_e32 v[68:69], v[52:53]
	v_mov_b64_e32 v[72:73], v[56:57]
	v_mov_b64_e32 v[76:77], v[60:61]
	v_mov_b64_e32 v[80:81], v[64:65]
	s_andn2_b64 vcc, exec, s[40:41]
	v_mov_b64_e32 v[66:67], v[50:51]
	v_mov_b64_e32 v[70:71], v[54:55]
	v_mov_b64_e32 v[74:75], v[58:59]
	v_mov_b64_e32 v[78:79], v[62:63]
	s_cbranch_vccnz .LBB0_441
	s_waitcnt vmcnt(3)
	v_mov_b64_e32 v[68:69], v[48:49]
	s_waitcnt vmcnt(2)
	v_mov_b64_e32 v[72:73], v[44:45]
	s_waitcnt vmcnt(1)
	v_mov_b64_e32 v[76:77], v[40:41]
	s_waitcnt vmcnt(0)
	v_mov_b64_e32 v[80:81], v[36:37]
	v_mov_b64_e32 v[66:67], v[46:47]
	v_mov_b64_e32 v[70:71], v[42:43]
	v_mov_b64_e32 v[74:75], v[38:39]
	v_mov_b64_e32 v[78:79], v[34:35]
.LBB0_441:
	s_mov_b64 s[96:97], 0x2c0000
	v_readlane_b32 s6, v255, 40
	v_readlane_b32 s88, v254, 41
	v_readlane_b32 s94, v254, 47
	v_readlane_b32 s95, v254, 48
	v_readlane_b32 s80, v254, 51
	v_readlane_b32 s86, v254, 39
	v_readlane_b32 s56, v254, 49
	v_readlane_b32 s81, v254, 52
	v_readlane_b32 s84, v254, 59
	v_readlane_b32 s94, v254, 61
	v_readlane_b32 s60, v254, 63
	v_readlane_b32 s76, v255, 15
	v_readlane_b32 s78, v255, 17
	v_readlane_b32 s58, v255, 33
	s_mov_b64 s[0:1], 0
	v_readlane_b32 s87, v254, 40
	v_readlane_b32 s89, v254, 42
	v_readlane_b32 s90, v254, 43
	v_readlane_b32 s91, v254, 44
	v_readlane_b32 s92, v254, 45
	v_readlane_b32 s93, v254, 46
	v_readlane_b32 s57, v254, 50
	v_readlane_b32 s85, v254, 60
	v_readlane_b32 s95, v254, 62
	v_readlane_b32 s61, v255, 0
	v_readlane_b32 s62, v255, 1
	v_readlane_b32 s63, v255, 2
	v_readlane_b32 s64, v255, 3
	v_readlane_b32 s65, v255, 4
	v_readlane_b32 s66, v255, 5
	v_readlane_b32 s67, v255, 6
	v_readlane_b32 s68, v255, 7
	v_readlane_b32 s69, v255, 8
	v_readlane_b32 s70, v255, 9
	v_readlane_b32 s71, v255, 10
	v_readlane_b32 s72, v255, 11
	v_readlane_b32 s73, v255, 12
	v_readlane_b32 s74, v255, 13
	v_readlane_b32 s75, v255, 14
	v_readlane_b32 s77, v255, 16
	v_readlane_b32 s79, v255, 18
	v_readlane_b32 s81, v254, 1
	s_mov_b64 s[82:83], 0x58000
	v_readlane_b32 s59, v255, 34
	v_readlane_b32 s40, v255, 60
	v_readlane_b32 s7, v255, 41
	v_readlane_b32 s41, v255, 61

; #define MFMA32(a, b, c) __builtin_amdgcn_mfma_f32_32x32x16_bf16((a), (b), (c), 0, 0, 0)
; DI void a1_task(unsigned char* shm, const bf16_t* prm, const bf16_t* prt, unsigned* mask, int b, int qt, const int tid) {
;     ...
;             for (int hh = 0; hh < 8; ++hh) {
;                 bf16x8 qa[4];
; #pragma unroll
;                 for (int ks = 0; ks < 4; ++ks) qa[ks] = *(const bf16x8*)(qb0 + hh * 128 + 32 * ks);
;                 const float wv = wqs[hh * 32 + r];
;                 asm volatile("s_waitcnt lgkmcnt(0)" ::: "memory");
;                 f32x16 acc;
; #pragma unroll
;                 for (int i = 0; i < 16; ++i) acc[i] = 0.f;
; #pragma unroll
;                 for (int ks = 0; ks < 4; ++ks) acc = MFMA32(kf[ks], qa[ks], acc);
; #pragma unroll
;                 for (int i = 0; i < 16; ++i) idx[i] = fmaf(wv, fmaxf(acc[i], 0.f), idx[i]);
;             }
; #pragma unroll
;             for (int i = 0; i < 16; ++i) {
;                 const int s = s0 + 16 * (i >> 3) + 8 * h + (i & 7);
;                 const unsigned u = __float_as_uint(idx[i] + 0.0f);
;                 const unsigned k = (u & 0x80000000u) ? ~u : (u | 0x80000000u);
;                 key[jt][i] = (s <= t0 + r) ? k : 0u;
;             }
.LBB0_448:
	v_add_u32_e32 v63, s1, v118
	ds_read_b128 v[2:5], v63
	ds_read_b128 v[50:53], v63 offset:32
	ds_read_b128 v[54:57], v63 offset:64
	ds_read_b128 v[58:61], v63 offset:96
	v_add_u32_e32 v64, s1, v135
	s_waitcnt lgkmcnt(3)
	v_mfma_f32_32x32x16_bf16 v[2:17], v[66:69], v[2:5], 0
	ds_read_b32 v62, v64
	s_waitcnt lgkmcnt(0)
	s_addk_i32 s1, 0x100
	s_cmpk_lg_i32 s1, 0x400
	s_waitcnt lgkmcnt(3)
	v_mfma_f32_32x32x16_bf16 v[2:17], v[70:73], v[50:53], v[2:17]
	s_waitcnt lgkmcnt(2)
	v_mfma_f32_32x32x16_bf16 v[2:17], v[74:77], v[54:57], v[2:17]
	s_waitcnt lgkmcnt(1)
	v_mfma_f32_32x32x16_bf16 v[2:17], v[78:81], v[58:61], v[2:17]
	s_nop 11
	v_max_f32_e32 v2, 0, v2
	v_max_f32_e32 v3, 0, v3
	s_waitcnt lgkmcnt(0)
	v_pk_fma_f32 v[32:33], v[62:63], v[2:3], v[32:33] op_sel_hi:[0,1,1]
	v_max_f32_e32 v2, 0, v4
	v_max_f32_e32 v3, 0, v5
	v_pk_fma_f32 v[30:31], v[62:63], v[2:3], v[30:31] op_sel_hi:[0,1,1]
	v_max_f32_e32 v2, 0, v6
	v_max_f32_e32 v3, 0, v7
	v_pk_fma_f32 v[28:29], v[62:63], v[2:3], v[28:29] op_sel_hi:[0,1,1]
	v_max_f32_e32 v2, 0, v8
	v_max_f32_e32 v3, 0, v9
	v_pk_fma_f32 v[26:27], v[62:63], v[2:3], v[26:27] op_sel_hi:[0,1,1]
	v_max_f32_e32 v2, 0, v10
	v_max_f32_e32 v3, 0, v11
	v_pk_fma_f32 v[24:25], v[62:63], v[2:3], v[24:25] op_sel_hi:[0,1,1]
	v_max_f32_e32 v2, 0, v12
	v_max_f32_e32 v3, 0, v13
	v_pk_fma_f32 v[22:23], v[62:63], v[2:3], v[22:23] op_sel_hi:[0,1,1]
	v_max_f32_e32 v2, 0, v14
	v_max_f32_e32 v3, 0, v15
	v_pk_fma_f32 v[20:21], v[62:63], v[2:3], v[20:21] op_sel_hi:[0,1,1]
	v_max_f32_e32 v2, 0, v16
	v_max_f32_e32 v3, 0, v17
	v_pk_fma_f32 v[18:19], v[62:63], v[2:3], v[18:19] op_sel_hi:[0,1,1]
	ds_read_b128 v[2:5], v63 offset:128
	ds_read_b128 v[50:53], v63 offset:160
	ds_read_b128 v[54:57], v63 offset:192
	ds_read_b128 v[58:61], v63 offset:224
	ds_read_b32 v62, v64 offset:128
	s_waitcnt lgkmcnt(4)
	v_mfma_f32_32x32x16_bf16 v[2:17], v[66:69], v[2:5], 0
	s_waitcnt lgkmcnt(0)
	s_waitcnt lgkmcnt(3)
	v_mfma_f32_32x32x16_bf16 v[2:17], v[70:73], v[50:53], v[2:17]
	s_waitcnt lgkmcnt(2)
	v_mfma_f32_32x32x16_bf16 v[2:17], v[74:77], v[54:57], v[2:17]
	s_waitcnt lgkmcnt(1)
	v_mfma_f32_32x32x16_bf16 v[2:17], v[78:81], v[58:61], v[2:17]
	s_nop 11
	v_max_f32_e32 v2, 0, v2
	v_max_f32_e32 v3, 0, v3
	s_waitcnt lgkmcnt(0)
	v_pk_fma_f32 v[32:33], v[62:63], v[2:3], v[32:33] op_sel_hi:[0,1,1]
	v_max_f32_e32 v2, 0, v4
	v_max_f32_e32 v3, 0, v5
	v_pk_fma_f32 v[30:31], v[62:63], v[2:3], v[30:31] op_sel_hi:[0,1,1]
	v_max_f32_e32 v2, 0, v6
	v_max_f32_e32 v3, 0, v7
	v_pk_fma_f32 v[28:29], v[62:63], v[2:3], v[28:29] op_sel_hi:[0,1,1]
	v_max_f32_e32 v2, 0, v8
	v_max_f32_e32 v3, 0, v9
	v_pk_fma_f32 v[26:27], v[62:63], v[2:3], v[26:27] op_sel_hi:[0,1,1]
	v_max_f32_e32 v2, 0, v10
	v_max_f32_e32 v3, 0, v11
	v_pk_fma_f32 v[24:25], v[62:63], v[2:3], v[24:25] op_sel_hi:[0,1,1]
	v_max_f32_e32 v2, 0, v12
	v_max_f32_e32 v3, 0, v13
	v_pk_fma_f32 v[22:23], v[62:63], v[2:3], v[22:23] op_sel_hi:[0,1,1]
	v_max_f32_e32 v2, 0, v14
	v_max_f32_e32 v3, 0, v15
	v_pk_fma_f32 v[20:21], v[62:63], v[2:3], v[20:21] op_sel_hi:[0,1,1]
	v_max_f32_e32 v2, 0, v16
	v_max_f32_e32 v3, 0, v17
	v_pk_fma_f32 v[18:19], v[62:63], v[2:3], v[18:19] op_sel_hi:[0,1,1]
	s_cbranch_scc1 .LBB0_448
	v_or_b32_e32 v8, s0, v98
	s_lshr_b32 s98, s0, 5
	s_cmp_lt_u32 s98, s2
	s_cbranch_scc1 .Lkc_full_448
	v_pk_add_f32 v[2:3], v[32:33], 0 op_sel_hi:[1,0]
	v_ashrrev_i32_e32 v4, 31, v2
	v_ashrrev_i32_e32 v5, 31, v3
	v_or_b32_e32 v4, 0x80000000, v4
	v_or_b32_e32 v5, 0x80000000, v5
	v_xor_b32_e32 v2, v2, v4
	v_xor_b32_e32 v3, v3, v5
	v_mov_b32_e32 v6, v8
	v_cmp_le_i32_e64 s[98:99], v6, v0
	v_or_b32_e32 v7, 1, v8
	s_nop 0
	v_cndmask_b32_e64 v51, 0, v2, s[98:99]
	v_cmp_le_i32_e64 s[98:99], v7, v0
	s_nop 1
	v_cndmask_b32_e64 v50, 0, v3, s[98:99]
	v_pk_add_f32 v[2:3], v[30:31], 0 op_sel_hi:[1,0]
	v_ashrrev_i32_e32 v4, 31, v2
	v_ashrrev_i32_e32 v5, 31, v3
	v_or_b32_e32 v4, 0x80000000, v4
	v_or_b32_e32 v5, 0x80000000, v5
	v_xor_b32_e32 v2, v2, v4
	v_xor_b32_e32 v3, v3, v5
	v_or_b32_e32 v6, 2, v8
	v_cmp_le_i32_e64 s[98:99], v6, v0
	v_or_b32_e32 v7, 3, v8
	s_nop 0
	v_cndmask_b32_e64 v53, 0, v2, s[98:99]
	v_cmp_le_i32_e64 s[98:99], v7, v0
	s_nop 1
	v_cndmask_b32_e64 v52, 0, v3, s[98:99]
	v_pk_add_f32 v[2:3], v[28:29], 0 op_sel_hi:[1,0]
	v_ashrrev_i32_e32 v4, 31, v2
	v_ashrrev_i32_e32 v5, 31, v3
	v_or_b32_e32 v4, 0x80000000, v4
	v_or_b32_e32 v5, 0x80000000, v5
	v_xor_b32_e32 v2, v2, v4
	v_xor_b32_e32 v3, v3, v5
	v_or_b32_e32 v6, 4, v8
	v_cmp_le_i32_e64 s[98:99], v6, v0
	v_or_b32_e32 v7, 5, v8
	s_nop 0
	v_cndmask_b32_e64 v55, 0, v2, s[98:99]
	v_cmp_le_i32_e64 s[98:99], v7, v0
	s_nop 1
	v_cndmask_b32_e64 v54, 0, v3, s[98:99]
	v_pk_add_f32 v[2:3], v[26:27], 0 op_sel_hi:[1,0]
	v_ashrrev_i32_e32 v4, 31, v2
	v_ashrrev_i32_e32 v5, 31, v3
	v_or_b32_e32 v4, 0x80000000, v4
	v_or_b32_e32 v5, 0x80000000, v5
	v_xor_b32_e32 v2, v2, v4
	v_xor_b32_e32 v3, v3, v5
	v_or_b32_e32 v6, 6, v8
	v_cmp_le_i32_e64 s[98:99], v6, v0
	v_or_b32_e32 v7, 7, v8
	s_nop 0
	v_cndmask_b32_e64 v57, 0, v2, s[98:99]
	v_cmp_le_i32_e64 s[98:99], v7, v0
	s_nop 1
	v_cndmask_b32_e64 v56, 0, v3, s[98:99]
	v_pk_add_f32 v[2:3], v[24:25], 0 op_sel_hi:[1,0]
	v_ashrrev_i32_e32 v4, 31, v2
	v_ashrrev_i32_e32 v5, 31, v3
	v_or_b32_e32 v4, 0x80000000, v4
	v_or_b32_e32 v5, 0x80000000, v5
	v_xor_b32_e32 v2, v2, v4
	v_xor_b32_e32 v3, v3, v5
	v_or_b32_e32 v6, 16, v8
	v_cmp_le_i32_e64 s[98:99], v6, v0
	v_or_b32_e32 v7, 17, v8
	s_nop 0
	v_cndmask_b32_e64 v59, 0, v2, s[98:99]
	v_cmp_le_i32_e64 s[98:99], v7, v0
	s_nop 1
	v_cndmask_b32_e64 v58, 0, v3, s[98:99]
	v_pk_add_f32 v[2:3], v[22:23], 0 op_sel_hi:[1,0]
	v_ashrrev_i32_e32 v4, 31, v2
	v_ashrrev_i32_e32 v5, 31, v3
	v_or_b32_e32 v4, 0x80000000, v4
	v_or_b32_e32 v5, 0x80000000, v5
	v_xor_b32_e32 v2, v2, v4
	v_xor_b32_e32 v3, v3, v5
	v_or_b32_e32 v6, 18, v8
	v_cmp_le_i32_e64 s[98:99], v6, v0
	v_or_b32_e32 v7, 19, v8
	s_nop 0
	v_cndmask_b32_e64 v61, 0, v2, s[98:99]
	v_cmp_le_i32_e64 s[98:99], v7, v0
	s_nop 1
	v_cndmask_b32_e64 v60, 0, v3, s[98:99]
	v_pk_add_f32 v[2:3], v[20:21], 0 op_sel_hi:[1,0]
	v_ashrrev_i32_e32 v4, 31, v2
	v_ashrrev_i32_e32 v5, 31, v3
	v_or_b32_e32 v4, 0x80000000, v4
	v_or_b32_e32 v5, 0x80000000, v5
	v_xor_b32_e32 v2, v2, v4
	v_xor_b32_e32 v3, v3, v5
	v_or_b32_e32 v6, 20, v8
	v_cmp_le_i32_e64 s[98:99], v6, v0
	v_or_b32_e32 v7, 21, v8
	s_nop 0
	v_cndmask_b32_e64 v63, 0, v2, s[98:99]
	v_cmp_le_i32_e64 s[98:99], v7, v0
	s_nop 1
	v_cndmask_b32_e64 v62, 0, v3, s[98:99]
	v_pk_add_f32 v[2:3], v[18:19], 0 op_sel_hi:[1,0]
	v_ashrrev_i32_e32 v4, 31, v2
	v_ashrrev_i32_e32 v5, 31, v3
	v_or_b32_e32 v4, 0x80000000, v4
	v_or_b32_e32 v5, 0x80000000, v5
	v_xor_b32_e32 v2, v2, v4
	v_xor_b32_e32 v3, v3, v5
	v_or_b32_e32 v6, 22, v8
	v_cmp_le_i32_e64 s[98:99], v6, v0
	v_or_b32_e32 v7, 23, v8
	s_nop 0
	v_cndmask_b32_e64 v65, 0, v2, s[98:99]
	v_cmp_le_i32_e64 s[98:99], v7, v0
	s_nop 1
	v_cndmask_b32_e64 v64, 0, v3, s[98:99]
	s_branch .Lkc_done_448
; DI void a1_task(unsigned char* shm, const bf16_t* prm, const bf16_t* prt, unsigned* mask, int b, int qt, const int tid) {
;     ...
;             for (int i = 0; i < 16; ++i) {
;                 const int s = s0 + 16 * (i >> 3) + 8 * h + (i & 7);
;                 const unsigned u = __float_as_uint(idx[i] + 0.0f);
;                 const unsigned k = (u & 0x80000000u) ? ~u : (u | 0x80000000u);
;                 key[jt][i] = (s <= t0 + r) ? k : 0u;
;             }
;             if (hn) {
; #pragma unroll
;                 for (int ks = 0; ks < 4; ++ks) kf[ks] = kn[ks];
.Lkc_full_448:
	v_pk_add_f32 v[2:3], v[32:33], 0 op_sel_hi:[1,0]
	v_ashrrev_i32_e32 v4, 31, v2
	v_ashrrev_i32_e32 v5, 31, v3
	v_or_b32_e32 v4, 0x80000000, v4
	v_or_b32_e32 v5, 0x80000000, v5
	v_xor_b32_e32 v51, v2, v4
	v_xor_b32_e32 v50, v3, v5
	v_pk_add_f32 v[2:3], v[30:31], 0 op_sel_hi:[1,0]
	v_ashrrev_i32_e32 v4, 31, v2
	v_ashrrev_i32_e32 v5, 31, v3
	v_or_b32_e32 v4, 0x80000000, v4
	v_or_b32_e32 v5, 0x80000000, v5
	v_xor_b32_e32 v53, v2, v4
	v_xor_b32_e32 v52, v3, v5
	v_pk_add_f32 v[2:3], v[28:29], 0 op_sel_hi:[1,0]
	v_ashrrev_i32_e32 v4, 31, v2
	v_ashrrev_i32_e32 v5, 31, v3
	v_or_b32_e32 v4, 0x80000000, v4
	v_or_b32_e32 v5, 0x80000000, v5
	v_xor_b32_e32 v55, v2, v4
	v_xor_b32_e32 v54, v3, v5
	v_pk_add_f32 v[2:3], v[26:27], 0 op_sel_hi:[1,0]
	v_ashrrev_i32_e32 v4, 31, v2
	v_ashrrev_i32_e32 v5, 31, v3
	v_or_b32_e32 v4, 0x80000000, v4
	v_or_b32_e32 v5, 0x80000000, v5
	v_xor_b32_e32 v57, v2, v4
	v_xor_b32_e32 v56, v3, v5
	v_pk_add_f32 v[2:3], v[24:25], 0 op_sel_hi:[1,0]
	v_ashrrev_i32_e32 v4, 31, v2
	v_ashrrev_i32_e32 v5, 31, v3
	v_or_b32_e32 v4, 0x80000000, v4
	v_or_b32_e32 v5, 0x80000000, v5
	v_xor_b32_e32 v59, v2, v4
	v_xor_b32_e32 v58, v3, v5
	v_pk_add_f32 v[2:3], v[22:23], 0 op_sel_hi:[1,0]
	v_ashrrev_i32_e32 v4, 31, v2
	v_ashrrev_i32_e32 v5, 31, v3
	v_or_b32_e32 v4, 0x80000000, v4
	v_or_b32_e32 v5, 0x80000000, v5
	v_xor_b32_e32 v61, v2, v4
	v_xor_b32_e32 v60, v3, v5
	v_pk_add_f32 v[2:3], v[20:21], 0 op_sel_hi:[1,0]
	v_ashrrev_i32_e32 v4, 31, v2
	v_ashrrev_i32_e32 v5, 31, v3
	v_or_b32_e32 v4, 0x80000000, v4
	v_or_b32_e32 v5, 0x80000000, v5
	v_xor_b32_e32 v63, v2, v4
	v_xor_b32_e32 v62, v3, v5
	v_pk_add_f32 v[2:3], v[18:19], 0 op_sel_hi:[1,0]
	v_ashrrev_i32_e32 v4, 31, v2
	v_ashrrev_i32_e32 v5, 31, v3
	v_or_b32_e32 v4, 0x80000000, v4
	v_or_b32_e32 v5, 0x80000000, v5
	v_xor_b32_e32 v65, v2, v4
	v_xor_b32_e32 v64, v3, v5
.Lkc_done_448:
	v_mov_b64_e32 v[18:19], v[66:67]
	v_mov_b64_e32 v[22:23], v[70:71]
	v_mov_b64_e32 v[26:27], v[74:75]
	v_mov_b64_e32 v[30:31], v[78:79]
	s_andn2_b64 vcc, exec, vcc
	v_mov_b64_e32 v[20:21], v[68:69]
	v_mov_b64_e32 v[24:25], v[72:73]
	v_mov_b64_e32 v[28:29], v[76:77]
	v_mov_b64_e32 v[32:33], v[80:81]
	s_cbranch_vccnz .LBB0_451
	s_waitcnt vmcnt(0)
	v_mov_b64_e32 v[18:19], v[46:47]
	v_mov_b64_e32 v[22:23], v[42:43]
	v_mov_b64_e32 v[26:27], v[38:39]
	v_mov_b64_e32 v[30:31], v[34:35]
	v_mov_b64_e32 v[20:21], v[48:49]
	v_mov_b64_e32 v[24:25], v[44:45]
	v_mov_b64_e32 v[28:29], v[40:41]
	v_mov_b64_e32 v[32:33], v[36:37]
.LBB0_451:
	s_mov_b64 s[96:97], 0x2c0000
	v_readlane_b32 s88, v254, 41
	v_readlane_b32 s94, v254, 47
	v_readlane_b32 s95, v254, 48
	v_readlane_b32 s80, v254, 51
	v_readlane_b32 s86, v254, 39
	v_readlane_b32 s56, v254, 49
	v_readlane_b32 s81, v254, 52
	v_readlane_b32 s84, v254, 59
	v_readlane_b32 s94, v254, 61
	v_readlane_b32 s60, v254, 63
	v_readlane_b32 s76, v255, 15
	v_readlane_b32 s78, v255, 17
	v_readlane_b32 s58, v255, 33
	s_mov_b64 s[0:1], 0
	v_readlane_b32 s87, v254, 40
	v_readlane_b32 s89, v254, 42
	v_readlane_b32 s90, v254, 43
	v_readlane_b32 s91, v254, 44
	v_readlane_b32 s92, v254, 45
	v_readlane_b32 s93, v254, 46
	v_readlane_b32 s57, v254, 50
	v_readlane_b32 s85, v254, 60
	v_readlane_b32 s95, v254, 62
	v_readlane_b32 s61, v255, 0
	v_readlane_b32 s62, v255, 1
	v_readlane_b32 s63, v255, 2
	v_readlane_b32 s64, v255, 3
	v_readlane_b32 s65, v255, 4
	v_readlane_b32 s66, v255, 5
	v_readlane_b32 s67, v255, 6
	v_readlane_b32 s68, v255, 7
	v_readlane_b32 s69, v255, 8
	v_readlane_b32 s70, v255, 9
	v_readlane_b32 s71, v255, 10
	v_readlane_b32 s72, v255, 11
	v_readlane_b32 s73, v255, 12
	v_readlane_b32 s74, v255, 13
	v_readlane_b32 s75, v255, 14
	v_readlane_b32 s77, v255, 16
	v_readlane_b32 s79, v255, 18
	v_readlane_b32 s81, v254, 1
	s_mov_b64 s[82:83], 0x58000
	v_readlane_b32 s59, v255, 34
